# defer the 8 row-sum atomics to the end of the EpiResid/EpiGlu epilogues (down-proj, GLU, even-out), on top of swiglu rs-load hoist
# speedup vs baseline: 1.0123x; 1.0123x over previous
.LBB0_281:
	v_lshl_add_u32 v136, s72, 8, v1
	v_ashrrev_i32_e32 v137, 31, v136
	v_lshl_add_u64 v[138:139], v[136:137], 3, s[42:43]
	global_load_dwordx2 v[168:169], v[138:139], off
	global_load_dwordx2 v[170:171], v[138:139], off offset:128
	global_load_dwordx2 v[172:173], v[138:139], off offset:256
	global_load_dwordx2 v[174:175], v[138:139], off offset:384
	global_load_dwordx2 v[176:177], v[138:139], off offset:1024
	global_load_dwordx2 v[178:179], v[138:139], off offset:1152
	global_load_dwordx2 v[180:181], v[138:139], off offset:1280
	global_load_dwordx2 v[182:183], v[138:139], off offset:1408
	v_mul_f32_e32 v148, v118, v114
	v_mul_f32_e32 v150, v120, v116
	v_mul_f32_e32 v149, v119, v115
	v_mul_f32_e32 v151, v121, v117
	v_mul_f32_e32 v137, v126, v122
	v_mul_f32_e32 v143, v127, v123
	v_mul_f32_e32 v128, v128, v124
	v_mul_f32_e32 v129, v129, v125
	v_readlane_b32 s14, v244, 60
	v_lshl_or_b32 v146, s74, 7, v141
	v_readlane_b32 s15, v244, 61
	v_ashrrev_i32_e32 v147, 31, v146
	v_mul_f32_e32 v112, v112, v108
	v_mul_f32_e32 v100, v100, v104
	v_mul_f32_e32 v101, v101, v105
	v_mul_f32_e32 v113, v113, v109
	v_mul_f32_e32 v96, v96, v92
	v_mul_f32_e32 v84, v84, v88
	v_mul_f32_e32 v85, v85, v89
	v_mul_f32_e32 v97, v97, v93
	v_mul_f32_e32 v80, v80, v76
	v_mul_f32_e32 v68, v68, v72
	v_mul_f32_e32 v69, v69, v73
	v_mul_f32_e32 v81, v81, v77
	v_mul_f32_e32 v64, v64, v60
	v_mul_f32_e32 v52, v52, v56
	v_mul_f32_e32 v53, v53, v57
	v_mul_f32_e32 v65, v65, v61
	v_mul_f32_e32 v48, v48, v44
	v_mul_f32_e32 v36, v36, v40
	v_mul_f32_e32 v37, v37, v41
	v_mul_f32_e32 v49, v49, v45
	v_mul_f32_e32 v32, v32, v28
	v_mul_f32_e32 v20, v20, v24
	v_mul_f32_e32 v21, v21, v25
	v_mul_f32_e32 v33, v33, v29
	v_mul_f32_e32 v14, v14, v10
	v_mul_f32_e32 v15, v15, v11
	v_mul_f32_e32 v16, v16, v12
	v_mul_f32_e32 v17, v17, v13
	v_mul_f32_e32 v8, v8, v4
	v_mul_f32_e32 v9, v9, v5
	s_andn2_b64 vcc, exec, s[68:69]
	v_readlane_b32 s47, v241, 8
	s_waitcnt vmcnt(7)
	v_ffbh_u32_e32 v118, v169
	v_min_u32_e32 v120, 32, v118
	v_lshlrev_b64 v[118:119], v120, v[168:169]
	v_min_u32_e32 v118, 1, v118
	v_or_b32_e32 v118, v119, v118
	v_cvt_f32_u32_e32 v121, v118
	v_sub_u32_e32 v120, 32, v120
	v_mov_b64_e32 v[118:119], s[14:15]
	v_mad_i64_i32 v[126:127], s[14:15], v136, s7, v[118:119]
	v_ldexp_f32 v120, v121, v120
	v_mul_f32_e32 v120, 0x35800000, v120
	v_fmamk_f32 v144, v120, 0x3a000000, v209
	v_rsq_f32_e32 v145, v144
	v_lshlrev_b64 v[120:121], 1, v[146:147]
	v_lshl_add_u64 v[126:127], v[126:127], 0, v[120:121]
	v_mul_f32_e32 v145, 0xbfb8aa3b, v145
	v_mul_f32_e32 v122, v122, v145
	v_mul_f32_e32 v123, v123, v145
	v_mul_f32_e32 v124, v124, v145
	v_mul_f32_e32 v125, v125, v145
	v_mul_f32_e32 v114, v114, v145
	v_mul_f32_e32 v115, v115, v145
	v_mul_f32_e32 v116, v116, v145
	v_mul_f32_e32 v117, v117, v145
	v_exp_f32_e32 v122, v122
	v_exp_f32_e32 v123, v123
	v_exp_f32_e32 v124, v124
	v_exp_f32_e32 v125, v125
	v_exp_f32_e32 v114, v114
	v_exp_f32_e32 v115, v115
	v_exp_f32_e32 v116, v116
	v_exp_f32_e32 v117, v117
	v_fma_f32 v122, v122, v144, v144
	v_fma_f32 v123, v123, v144, v144
	v_fma_f32 v124, v124, v144, v144
	v_fma_f32 v125, v125, v144, v144
	v_fma_f32 v114, v114, v144, v144
	v_fma_f32 v115, v115, v144, v144
	v_fma_f32 v116, v116, v144, v144
	v_fmac_f32_e32 v144, v117, v144
	v_rcp_f32_e32 v117, v122
	v_rcp_f32_e32 v122, v123
	v_rcp_f32_e32 v123, v124
	v_rcp_f32_e32 v124, v125
	v_rcp_f32_e32 v114, v114
	v_rcp_f32_e32 v115, v115
	v_rcp_f32_e32 v116, v116
	v_rcp_f32_e32 v125, v144
	v_mul_f32_e32 v117, v137, v117
	v_mul_f32_e32 v122, v143, v122
	v_mul_f32_e32 v123, v128, v123
	v_mul_f32_e32 v124, v129, v124
	v_mul_f32_e32 v128, v148, v114
	v_mul_f32_e32 v129, v149, v115
	v_mul_f32_e32 v137, v150, v116
	v_mul_f32_e32 v125, v151, v125
	v_cvt_pk_bf16_f32 v114, v117, v122
	v_cvt_pk_bf16_f32 v115, v123, v124
	v_cvt_pk_bf16_f32 v116, v128, v129
	v_cvt_pk_bf16_f32 v117, v137, v125
	global_store_dwordx4 v[126:127], v[114:117], off
	s_nop 0
	v_mul_f32_e32 v122, v98, v102
	v_mul_f32_e32 v116, v110, v106
	v_mul_f32_e32 v123, v99, v103
	v_mul_f32_e32 v117, v111, v107
	s_waitcnt vmcnt(7)
	v_ffbh_u32_e32 v98, v171
	v_min_u32_e32 v110, 32, v98
	v_lshlrev_b64 v[98:99], v110, v[170:171]
	v_min_u32_e32 v98, 1, v98
	v_or_b32_e32 v98, v99, v98
	v_cvt_f32_u32_e32 v98, v98
	v_sub_u32_e32 v110, 32, v110
	v_or_b32_e32 v99, 16, v136
	v_ldexp_f32 v98, v98, v110
	v_mul_f32_e32 v98, 0x35800000, v98
	v_fmamk_f32 v114, v98, 0x3a000000, v209
	v_rsq_f32_e32 v115, v114
	v_mad_i64_i32 v[98:99], s[14:15], v99, s7, v[118:119]
	v_lshl_add_u64 v[110:111], v[98:99], 0, v[120:121]
	v_mul_f32_e32 v98, 0xbfb8aa3b, v115
	v_mul_f32_e32 v99, v106, v98
	v_mul_f32_e32 v106, v107, v98
	v_mul_f32_e32 v107, v108, v98
	v_mul_f32_e32 v108, v109, v98
	v_mul_f32_e32 v102, v102, v98
	v_mul_f32_e32 v103, v103, v98
	v_mul_f32_e32 v104, v104, v98
	v_mul_f32_e32 v98, v105, v98
	v_exp_f32_e32 v99, v99
	v_exp_f32_e32 v105, v106
	v_exp_f32_e32 v106, v107
	v_exp_f32_e32 v107, v108
	v_exp_f32_e32 v102, v102
	v_exp_f32_e32 v103, v103
	v_exp_f32_e32 v104, v104
	v_exp_f32_e32 v98, v98
	v_fma_f32 v99, v99, v114, v114
	v_fma_f32 v105, v105, v114, v114
	v_fma_f32 v106, v106, v114, v114
	v_fma_f32 v107, v107, v114, v114
	v_fma_f32 v102, v102, v114, v114
	v_fma_f32 v103, v103, v114, v114
	v_fma_f32 v104, v104, v114, v114
	v_fmac_f32_e32 v114, v98, v114
	v_rcp_f32_e32 v98, v99
	v_rcp_f32_e32 v99, v105
	v_rcp_f32_e32 v105, v106
	v_rcp_f32_e32 v106, v107
	v_rcp_f32_e32 v107, v114
	v_rcp_f32_e32 v102, v102
	v_rcp_f32_e32 v103, v103
	v_rcp_f32_e32 v104, v104
	v_mul_f32_e32 v98, v116, v98
	v_mul_f32_e32 v99, v117, v99
	v_mul_f32_e32 v101, v101, v107
	v_mul_f32_e32 v105, v112, v105
	v_mul_f32_e32 v106, v113, v106
	v_mul_f32_e32 v102, v122, v102
	v_mul_f32_e32 v103, v123, v103
	v_mul_f32_e32 v104, v100, v104
	v_cvt_pk_bf16_f32 v98, v98, v99
	v_cvt_pk_bf16_f32 v99, v105, v106
	v_cvt_pk_bf16_f32 v100, v102, v103
	v_cvt_pk_bf16_f32 v101, v104, v101
	global_store_dwordx4 v[110:111], v[98:101], off
	s_nop 0
	v_mul_f32_e32 v102, v82, v86
	v_mul_f32_e32 v100, v94, v90
	v_mul_f32_e32 v103, v83, v87
	v_mul_f32_e32 v101, v95, v91
	s_waitcnt vmcnt(7)
	v_ffbh_u32_e32 v82, v173
	v_min_u32_e32 v94, 32, v82
	v_lshlrev_b64 v[82:83], v94, v[172:173]
	v_min_u32_e32 v82, 1, v82
	v_or_b32_e32 v82, v83, v82
	v_cvt_f32_u32_e32 v82, v82
	v_sub_u32_e32 v94, 32, v94
	v_or_b32_e32 v83, 32, v136
	v_ldexp_f32 v82, v82, v94
	v_mul_f32_e32 v82, 0x35800000, v82
	v_fmamk_f32 v98, v82, 0x3a000000, v209
	v_rsq_f32_e32 v99, v98
	v_mad_i64_i32 v[82:83], s[14:15], v83, s7, v[118:119]
	v_lshl_add_u64 v[94:95], v[82:83], 0, v[120:121]
	v_mul_f32_e32 v82, 0xbfb8aa3b, v99
	v_mul_f32_e32 v83, v90, v82
	v_mul_f32_e32 v90, v91, v82
	v_mul_f32_e32 v91, v92, v82
	v_mul_f32_e32 v92, v93, v82
	v_mul_f32_e32 v86, v86, v82
	v_mul_f32_e32 v87, v87, v82
	v_mul_f32_e32 v88, v88, v82
	v_mul_f32_e32 v82, v89, v82
	v_exp_f32_e32 v83, v83
	v_exp_f32_e32 v89, v90
	v_exp_f32_e32 v90, v91
	v_exp_f32_e32 v91, v92
	v_exp_f32_e32 v86, v86
	v_exp_f32_e32 v87, v87
	v_exp_f32_e32 v88, v88
	v_exp_f32_e32 v82, v82
	v_fma_f32 v83, v83, v98, v98
	v_fma_f32 v89, v89, v98, v98
	v_fma_f32 v90, v90, v98, v98
	v_fma_f32 v91, v91, v98, v98
	v_fma_f32 v86, v86, v98, v98
	v_fma_f32 v87, v87, v98, v98
	v_fma_f32 v88, v88, v98, v98
	v_fmac_f32_e32 v98, v82, v98
	v_rcp_f32_e32 v82, v83
	v_rcp_f32_e32 v83, v89
	v_rcp_f32_e32 v89, v90
	v_rcp_f32_e32 v90, v91
	v_rcp_f32_e32 v91, v98
	v_rcp_f32_e32 v86, v86
	v_rcp_f32_e32 v87, v87
	v_rcp_f32_e32 v88, v88
	v_mul_f32_e32 v82, v100, v82
	v_mul_f32_e32 v83, v101, v83
	v_mul_f32_e32 v85, v85, v91
	v_mul_f32_e32 v89, v96, v89
	v_mul_f32_e32 v90, v97, v90
	v_mul_f32_e32 v86, v102, v86
	v_mul_f32_e32 v87, v103, v87
	v_mul_f32_e32 v88, v84, v88
	v_cvt_pk_bf16_f32 v82, v82, v83
	v_cvt_pk_bf16_f32 v83, v89, v90
	v_cvt_pk_bf16_f32 v84, v86, v87
	v_cvt_pk_bf16_f32 v85, v88, v85
	global_store_dwordx4 v[94:95], v[82:85], off
	s_nop 0
	v_mul_f32_e32 v86, v66, v70
	v_mul_f32_e32 v84, v78, v74
	v_mul_f32_e32 v87, v67, v71
	v_mul_f32_e32 v85, v79, v75
	s_waitcnt vmcnt(7)
	v_ffbh_u32_e32 v66, v175
	v_min_u32_e32 v78, 32, v66
	v_lshlrev_b64 v[66:67], v78, v[174:175]
	v_min_u32_e32 v66, 1, v66
	v_or_b32_e32 v66, v67, v66
	v_cvt_f32_u32_e32 v66, v66
	v_sub_u32_e32 v78, 32, v78
	v_or_b32_e32 v67, 48, v136
	v_ldexp_f32 v66, v66, v78
	v_mul_f32_e32 v66, 0x35800000, v66
	v_fmamk_f32 v82, v66, 0x3a000000, v209
	v_rsq_f32_e32 v83, v82
	v_mad_i64_i32 v[66:67], s[14:15], v67, s7, v[118:119]
	v_lshl_add_u64 v[78:79], v[66:67], 0, v[120:121]
	v_mul_f32_e32 v66, 0xbfb8aa3b, v83
	v_mul_f32_e32 v67, v74, v66
	v_mul_f32_e32 v74, v75, v66
	v_mul_f32_e32 v75, v76, v66
	v_mul_f32_e32 v76, v77, v66
	v_mul_f32_e32 v70, v70, v66
	v_mul_f32_e32 v71, v71, v66
	v_mul_f32_e32 v72, v72, v66
	v_mul_f32_e32 v66, v73, v66
	v_exp_f32_e32 v67, v67
	v_exp_f32_e32 v73, v74
	v_exp_f32_e32 v74, v75
	v_exp_f32_e32 v75, v76
	v_exp_f32_e32 v70, v70
	v_exp_f32_e32 v71, v71
	v_exp_f32_e32 v72, v72
	v_exp_f32_e32 v66, v66
	v_fma_f32 v67, v67, v82, v82
	v_fma_f32 v73, v73, v82, v82
	v_fma_f32 v74, v74, v82, v82
	v_fma_f32 v75, v75, v82, v82
	v_fma_f32 v70, v70, v82, v82
	v_fma_f32 v71, v71, v82, v82
	v_fma_f32 v72, v72, v82, v82
	v_fmac_f32_e32 v82, v66, v82
	v_rcp_f32_e32 v66, v67
	v_rcp_f32_e32 v67, v73
	v_rcp_f32_e32 v73, v74
	v_rcp_f32_e32 v74, v75
	v_rcp_f32_e32 v75, v82
	v_rcp_f32_e32 v70, v70
	v_rcp_f32_e32 v71, v71
	v_rcp_f32_e32 v72, v72
	v_mul_f32_e32 v66, v84, v66
	v_mul_f32_e32 v67, v85, v67
	v_mul_f32_e32 v69, v69, v75
	v_mul_f32_e32 v73, v80, v73
	v_mul_f32_e32 v74, v81, v74
	v_mul_f32_e32 v70, v86, v70
	v_mul_f32_e32 v71, v87, v71
	v_mul_f32_e32 v72, v68, v72
	v_cvt_pk_bf16_f32 v66, v66, v67
	v_cvt_pk_bf16_f32 v67, v73, v74
	v_cvt_pk_bf16_f32 v68, v70, v71
	v_cvt_pk_bf16_f32 v69, v72, v69
	global_store_dwordx4 v[78:79], v[66:69], off
	s_nop 0
	v_mul_f32_e32 v70, v50, v54
	v_mul_f32_e32 v68, v62, v58
	v_mul_f32_e32 v71, v51, v55
	v_mul_f32_e32 v69, v63, v59
	s_waitcnt vmcnt(7)
	v_ffbh_u32_e32 v50, v177
	v_min_u32_e32 v62, 32, v50
	v_lshlrev_b64 v[50:51], v62, v[176:177]
	v_min_u32_e32 v50, 1, v50
	v_or_b32_e32 v50, v51, v50
	v_cvt_f32_u32_e32 v50, v50
	v_sub_u32_e32 v62, 32, v62
	v_add_u32_e32 v51, 0x80, v136
	v_ldexp_f32 v50, v50, v62
	v_mul_f32_e32 v50, 0x35800000, v50
	v_fmamk_f32 v66, v50, 0x3a000000, v209
	v_rsq_f32_e32 v67, v66
	v_mad_i64_i32 v[50:51], s[14:15], v51, s7, v[118:119]
	v_lshl_add_u64 v[62:63], v[50:51], 0, v[120:121]
	v_mul_f32_e32 v50, 0xbfb8aa3b, v67
	v_mul_f32_e32 v51, v58, v50
	v_mul_f32_e32 v58, v59, v50
	v_mul_f32_e32 v59, v60, v50
	v_mul_f32_e32 v60, v61, v50
	v_mul_f32_e32 v54, v54, v50
	v_mul_f32_e32 v55, v55, v50
	v_mul_f32_e32 v56, v56, v50
	v_mul_f32_e32 v50, v57, v50
	v_exp_f32_e32 v51, v51
	v_exp_f32_e32 v57, v58
	v_exp_f32_e32 v58, v59
	v_exp_f32_e32 v59, v60
	v_exp_f32_e32 v54, v54
	v_exp_f32_e32 v55, v55
	v_exp_f32_e32 v56, v56
	v_exp_f32_e32 v50, v50
	v_fma_f32 v51, v51, v66, v66
	v_fma_f32 v57, v57, v66, v66
	v_fma_f32 v58, v58, v66, v66
	v_fma_f32 v59, v59, v66, v66
	v_fma_f32 v54, v54, v66, v66
	v_fma_f32 v55, v55, v66, v66
	v_fma_f32 v56, v56, v66, v66
	v_fmac_f32_e32 v66, v50, v66
	v_rcp_f32_e32 v50, v51
	v_rcp_f32_e32 v51, v57
	v_rcp_f32_e32 v57, v58
	v_rcp_f32_e32 v58, v59
	v_rcp_f32_e32 v59, v66
	v_rcp_f32_e32 v54, v54
	v_rcp_f32_e32 v55, v55
	v_rcp_f32_e32 v56, v56
	v_mul_f32_e32 v50, v68, v50
	v_mul_f32_e32 v51, v69, v51
	v_mul_f32_e32 v53, v53, v59
	v_mul_f32_e32 v57, v64, v57
	v_mul_f32_e32 v58, v65, v58
	v_mul_f32_e32 v54, v70, v54
	v_mul_f32_e32 v55, v71, v55
	v_mul_f32_e32 v56, v52, v56
	v_cvt_pk_bf16_f32 v50, v50, v51
	v_cvt_pk_bf16_f32 v51, v57, v58
	v_cvt_pk_bf16_f32 v52, v54, v55
	v_cvt_pk_bf16_f32 v53, v56, v53
	global_store_dwordx4 v[62:63], v[50:53], off
	s_nop 0
	v_mul_f32_e32 v54, v34, v38
	v_mul_f32_e32 v52, v46, v42
	v_mul_f32_e32 v55, v35, v39
	v_mul_f32_e32 v53, v47, v43
	s_waitcnt vmcnt(7)
	v_ffbh_u32_e32 v34, v179
	v_min_u32_e32 v46, 32, v34
	v_lshlrev_b64 v[34:35], v46, v[178:179]
	v_min_u32_e32 v34, 1, v34
	v_or_b32_e32 v34, v35, v34
	v_cvt_f32_u32_e32 v34, v34
	v_sub_u32_e32 v46, 32, v46
	v_add_u32_e32 v35, 0x90, v136
	v_ldexp_f32 v34, v34, v46
	v_mul_f32_e32 v34, 0x35800000, v34
	v_fmamk_f32 v50, v34, 0x3a000000, v209
	v_rsq_f32_e32 v51, v50
	v_mad_i64_i32 v[34:35], s[14:15], v35, s7, v[118:119]
	v_lshl_add_u64 v[46:47], v[34:35], 0, v[120:121]
	v_mul_f32_e32 v34, 0xbfb8aa3b, v51
	v_mul_f32_e32 v35, v42, v34
	v_mul_f32_e32 v42, v43, v34
	v_mul_f32_e32 v43, v44, v34
	v_mul_f32_e32 v44, v45, v34
	v_mul_f32_e32 v38, v38, v34
	v_mul_f32_e32 v39, v39, v34
	v_mul_f32_e32 v40, v40, v34
	v_mul_f32_e32 v34, v41, v34
	v_exp_f32_e32 v35, v35
	v_exp_f32_e32 v41, v42
	v_exp_f32_e32 v42, v43
	v_exp_f32_e32 v43, v44
	v_exp_f32_e32 v38, v38
	v_exp_f32_e32 v39, v39
	v_exp_f32_e32 v40, v40
	v_exp_f32_e32 v34, v34
	v_fma_f32 v35, v35, v50, v50
	v_fma_f32 v41, v41, v50, v50
	v_fma_f32 v42, v42, v50, v50
	v_fma_f32 v43, v43, v50, v50
	v_fma_f32 v38, v38, v50, v50
	v_fma_f32 v39, v39, v50, v50
	v_fma_f32 v40, v40, v50, v50
	v_fmac_f32_e32 v50, v34, v50
	v_rcp_f32_e32 v34, v35
	v_rcp_f32_e32 v35, v41
	v_rcp_f32_e32 v41, v42
	v_rcp_f32_e32 v42, v43
	v_rcp_f32_e32 v43, v50
	v_rcp_f32_e32 v38, v38
	v_rcp_f32_e32 v39, v39
	v_rcp_f32_e32 v40, v40
	v_mul_f32_e32 v34, v52, v34
	v_mul_f32_e32 v35, v53, v35
	v_mul_f32_e32 v37, v37, v43
	v_mul_f32_e32 v41, v48, v41
	v_mul_f32_e32 v42, v49, v42
	v_mul_f32_e32 v38, v54, v38
	v_mul_f32_e32 v39, v55, v39
	v_mul_f32_e32 v40, v36, v40
	v_cvt_pk_bf16_f32 v34, v34, v35
	v_cvt_pk_bf16_f32 v35, v41, v42
	v_cvt_pk_bf16_f32 v36, v38, v39
	v_cvt_pk_bf16_f32 v37, v40, v37
	global_store_dwordx4 v[46:47], v[34:37], off
	s_nop 0
	v_mul_f32_e32 v38, v18, v22
	v_mul_f32_e32 v36, v30, v26
	v_mul_f32_e32 v39, v19, v23
	v_mul_f32_e32 v37, v31, v27
	s_waitcnt vmcnt(7)
	v_ffbh_u32_e32 v18, v181
	v_min_u32_e32 v30, 32, v18
	v_lshlrev_b64 v[18:19], v30, v[180:181]
	v_min_u32_e32 v18, 1, v18
	v_or_b32_e32 v18, v19, v18
	v_cvt_f32_u32_e32 v18, v18
	v_sub_u32_e32 v30, 32, v30
	v_add_u32_e32 v19, 0xa0, v136
	v_ldexp_f32 v18, v18, v30
	v_mul_f32_e32 v18, 0x35800000, v18
	v_fmamk_f32 v34, v18, 0x3a000000, v209
	v_rsq_f32_e32 v35, v34
	v_mad_i64_i32 v[18:19], s[14:15], v19, s7, v[118:119]
	v_lshl_add_u64 v[30:31], v[18:19], 0, v[120:121]
	v_mul_f32_e32 v18, 0xbfb8aa3b, v35
	v_mul_f32_e32 v19, v26, v18
	v_mul_f32_e32 v26, v27, v18
	v_mul_f32_e32 v27, v28, v18
	v_mul_f32_e32 v28, v29, v18
	v_mul_f32_e32 v22, v22, v18
	v_mul_f32_e32 v23, v23, v18
	v_mul_f32_e32 v24, v24, v18
	v_mul_f32_e32 v18, v25, v18
	v_exp_f32_e32 v19, v19
	v_exp_f32_e32 v25, v26
	v_exp_f32_e32 v26, v27
	v_exp_f32_e32 v27, v28
	v_exp_f32_e32 v22, v22
	v_exp_f32_e32 v23, v23
	v_exp_f32_e32 v24, v24
	v_exp_f32_e32 v18, v18
	v_fma_f32 v19, v19, v34, v34
	v_fma_f32 v25, v25, v34, v34
	v_fma_f32 v26, v26, v34, v34
	v_fma_f32 v27, v27, v34, v34
	v_fma_f32 v22, v22, v34, v34
	v_fma_f32 v23, v23, v34, v34
	v_fma_f32 v24, v24, v34, v34
	v_fmac_f32_e32 v34, v18, v34
	v_rcp_f32_e32 v18, v19
	v_rcp_f32_e32 v19, v25
	v_rcp_f32_e32 v25, v26
	v_rcp_f32_e32 v26, v27
	v_rcp_f32_e32 v27, v34
	v_rcp_f32_e32 v22, v22
	v_rcp_f32_e32 v23, v23
	v_rcp_f32_e32 v24, v24
	v_mul_f32_e32 v18, v36, v18
	v_mul_f32_e32 v19, v37, v19
	v_mul_f32_e32 v21, v21, v27
	v_mul_f32_e32 v25, v32, v25
	v_mul_f32_e32 v26, v33, v26
	v_mul_f32_e32 v22, v38, v22
	v_mul_f32_e32 v23, v39, v23
	v_mul_f32_e32 v24, v20, v24
	v_cvt_pk_bf16_f32 v18, v18, v19
	v_cvt_pk_bf16_f32 v19, v25, v26
	v_cvt_pk_bf16_f32 v20, v22, v23
	v_cvt_pk_bf16_f32 v21, v24, v21
	global_store_dwordx4 v[30:31], v[18:21], off
	s_nop 0
	s_nop 0
	v_mul_f32_e32 v20, v6, v2
	v_mul_f32_e32 v21, v7, v3
	s_waitcnt vmcnt(7)
	v_ffbh_u32_e32 v6, v183
	v_min_u32_e32 v22, 32, v6
	v_lshlrev_b64 v[6:7], v22, v[182:183]
	v_min_u32_e32 v6, 1, v6
	v_or_b32_e32 v6, v7, v6
	v_cvt_f32_u32_e32 v6, v6
	v_sub_u32_e32 v18, 32, v22
	v_add_u32_e32 v7, 0xb0, v136
	v_ldexp_f32 v6, v6, v18
	v_mul_f32_e32 v6, 0x35800000, v6
	v_fmamk_f32 v18, v6, 0x3a000000, v209
	v_rsq_f32_e32 v19, v18
	v_mad_i64_i32 v[6:7], s[14:15], v7, s7, v[118:119]
	v_lshl_add_u64 v[6:7], v[6:7], 0, v[120:121]
	v_mul_f32_e32 v19, 0xbfb8aa3b, v19
	v_mul_f32_e32 v10, v10, v19
	v_mul_f32_e32 v11, v11, v19
	v_mul_f32_e32 v12, v12, v19
	v_mul_f32_e32 v13, v13, v19
	v_mul_f32_e32 v2, v2, v19
	v_mul_f32_e32 v3, v3, v19
	v_mul_f32_e32 v4, v4, v19
	v_mul_f32_e32 v5, v5, v19
	v_exp_f32_e32 v10, v10
	v_exp_f32_e32 v11, v11
	v_exp_f32_e32 v12, v12
	v_exp_f32_e32 v13, v13
	v_exp_f32_e32 v2, v2
	v_exp_f32_e32 v3, v3
	v_exp_f32_e32 v4, v4
	v_exp_f32_e32 v5, v5
	v_fma_f32 v10, v10, v18, v18
	v_fma_f32 v11, v11, v18, v18
	v_fma_f32 v12, v12, v18, v18
	v_fma_f32 v13, v13, v18, v18
	v_fma_f32 v2, v2, v18, v18
	v_fma_f32 v3, v3, v18, v18
	v_fma_f32 v4, v4, v18, v18
	v_fmac_f32_e32 v18, v5, v18
	v_rcp_f32_e32 v5, v10
	v_rcp_f32_e32 v10, v11
	v_rcp_f32_e32 v11, v12
	v_rcp_f32_e32 v12, v13
	v_rcp_f32_e32 v2, v2
	v_rcp_f32_e32 v3, v3
	v_rcp_f32_e32 v4, v4
	v_rcp_f32_e32 v13, v18
	v_mul_f32_e32 v5, v14, v5
	s_mov_b64 s[14:15], -1
	v_mul_f32_e32 v10, v15, v10
	v_mul_f32_e32 v11, v16, v11
	v_mul_f32_e32 v12, v17, v12
	v_mul_f32_e32 v14, v20, v2
	v_mul_f32_e32 v15, v21, v3
	v_mul_f32_e32 v8, v8, v4
	v_mul_f32_e32 v9, v9, v13
	v_cvt_pk_bf16_f32 v2, v5, v10
	v_cvt_pk_bf16_f32 v3, v11, v12
	v_cvt_pk_bf16_f32 v4, v14, v15
	v_cvt_pk_bf16_f32 v5, v8, v9
	global_store_dwordx4 v[6:7], v[2:5], off
	s_cbranch_vccnz .LBB0_256
	s_andn2_b64 vcc, exec, s[20:21]
	s_cbranch_vccnz .LBB0_255
	s_barrier
	s_branch .LBB0_255

.LBB0_356:
	v_lshl_add_u32 v144, s11, 8, v1
	v_ashrrev_i32_e32 v145, 31, v144
	v_lshl_or_b32 v142, s10, 8, v147
	v_lshlrev_b64 v[140:141], 12, v[144:145]
	v_ashrrev_i32_e32 v143, 31, v142
	v_lshl_add_u64 v[140:141], s[94:95], 0, v[140:141]
	v_lshl_add_u64 v[140:141], v[142:143], 1, v[140:141]
	global_load_dwordx4 v[150:153], v[140:141], off
	s_waitcnt vmcnt(0)
	v_lshlrev_b32_e32 v149, 16, v150
	v_and_b32_e32 v150, 0xffff0000, v150
	v_lshlrev_b32_e32 v154, 16, v151
	v_and_b32_e32 v151, 0xffff0000, v151
	v_lshlrev_b32_e32 v155, 16, v152
	v_and_b32_e32 v152, 0xffff0000, v152
	v_lshlrev_b32_e32 v156, 16, v153
	v_and_b32_e32 v153, 0xffff0000, v153
	v_fmac_f32_e32 v150, 0.5, v127
	v_fmac_f32_e32 v151, 0.5, v129
	v_fmac_f32_e32 v152, 0.5, v123
	v_fmac_f32_e32 v153, 0.5, v125
	v_fmac_f32_e32 v149, 0.5, v126
	v_fmac_f32_e32 v154, 0.5, v128
	v_fmac_f32_e32 v155, 0.5, v122
	v_fmac_f32_e32 v156, 0.5, v124
	v_cvt_pk_bf16_f32 v124, v149, v150
	v_cvt_pk_bf16_f32 v125, v154, v151
	v_cvt_pk_bf16_f32 v126, v155, v152
	v_cvt_pk_bf16_f32 v127, v156, v153
	global_load_dwordx4 v[150:153], v[140:141], off offset:256
	v_lshlrev_b32_e32 v128, 16, v124
	global_store_dwordx4 v[140:141], v[124:127], off
	v_lshlrev_b32_e32 v129, 16, v125
	v_lshlrev_b32_e32 v149, 16, v126
	v_and_b32_e32 v124, 0xffff0000, v124
	v_and_b32_e32 v125, 0xffff0000, v125
	v_and_b32_e32 v126, 0xffff0000, v126
	v_lshlrev_b32_e32 v154, 16, v127
	v_and_b32_e32 v127, 0xffff0000, v127
	v_mul_f32_e32 v124, v124, v124
	v_mul_f32_e32 v125, v125, v125
	v_mul_f32_e32 v126, v126, v126
	v_mul_f32_e32 v127, v127, v127
	v_fmac_f32_e32 v124, v128, v128
	v_fmac_f32_e32 v125, v129, v129
	v_fmac_f32_e32 v126, v149, v149
	v_fmac_f32_e32 v127, v154, v154
	v_add_f32_e32 v124, v124, v125
	v_add_f32_e32 v125, v126, v127
	v_add_f32_e32 v128, v124, v125
	v_and_b32_e32 v123, 64, v212
	v_xor_b32_e32 v122, 16, v212
	v_add_u32_e32 v123, 64, v123
	v_cmp_lt_i32_e32 vcc, v122, v123
	s_waitcnt vmcnt(1)
	v_lshlrev_b32_e32 v124, 16, v150
	v_and_b32_e32 v125, 0xffff0000, v150
	v_lshlrev_b32_e32 v126, 16, v151
	v_and_b32_e32 v127, 0xffff0000, v151
	v_lshlrev_b32_e32 v129, 16, v152
	v_and_b32_e32 v149, 0xffff0000, v152
	v_lshlrev_b32_e32 v150, 16, v153
	v_and_b32_e32 v151, 0xffff0000, v153
	v_fmac_f32_e32 v124, 0.5, v118
	v_fmac_f32_e32 v125, 0.5, v119
	v_fmac_f32_e32 v126, 0.5, v120
	v_fmac_f32_e32 v127, 0.5, v121
	v_fmac_f32_e32 v129, 0.5, v114
	v_fmac_f32_e32 v149, 0.5, v115
	v_fmac_f32_e32 v150, 0.5, v116
	v_fmac_f32_e32 v151, 0.5, v117
	v_cvt_pk_bf16_f32 v124, v124, v125
	v_cvt_pk_bf16_f32 v125, v126, v127
	v_cvt_pk_bf16_f32 v126, v129, v149
	v_cvt_pk_bf16_f32 v127, v150, v151
	v_cndmask_b32_e32 v122, v212, v122, vcc
	v_and_b32_e32 v115, 0xffff0000, v124
	v_and_b32_e32 v117, 0xffff0000, v125
	v_and_b32_e32 v119, 0xffff0000, v126
	v_and_b32_e32 v121, 0xffff0000, v127
	v_lshlrev_b32_e32 v114, 16, v124
	v_lshlrev_b32_e32 v116, 16, v125
	v_lshlrev_b32_e32 v118, 16, v126
	v_lshlrev_b32_e32 v120, 16, v127
	v_mul_f32_e32 v115, v115, v115
	v_mul_f32_e32 v117, v117, v117
	v_mul_f32_e32 v119, v119, v119
	v_mul_f32_e32 v121, v121, v121
	v_fmac_f32_e32 v115, v114, v114
	v_fmac_f32_e32 v117, v116, v116
	v_fmac_f32_e32 v119, v118, v118
	v_fmac_f32_e32 v121, v120, v120
	v_add_f32_e32 v114, v115, v117
	v_add_f32_e32 v115, v119, v121
	v_add_f32_e32 v114, v114, v115
	v_lshlrev_b32_e32 v122, 2, v122
	v_add_f32_e32 v114, v128, v114
	ds_bpermute_b32 v115, v122, v114
	v_xor_b32_e32 v116, 32, v212
	v_cmp_lt_i32_e32 vcc, v116, v123
	global_store_dwordx4 v[140:141], v[124:127], off offset:256
	s_waitcnt lgkmcnt(0)
	v_add_f32_e32 v117, v114, v115
	v_cndmask_b32_e32 v116, v212, v116, vcc
	v_lshlrev_b32_e32 v116, 2, v116
	ds_bpermute_b32 v118, v116, v117
	v_lshl_add_u64 v[114:115], v[144:145], 3, s[8:9]
	s_and_saveexec_b64 s[0:1], s[40:41]
	s_cbranch_execz .LBB0_358
	s_waitcnt lgkmcnt(0)
	v_add_f32_e32 v117, v117, v118
	v_fma_f32 v117, v117, s6, 0.5
	v_trunc_f32_e32 v117, v117
	v_mul_f32_e32 v118, 0x2f800000, v117
	v_floor_f32_e32 v119, v118
	v_fmac_f32_e32 v117, 0xcf800000, v119
	v_cvt_u32_f32_e32 v118, v117
	v_cvt_u32_f32_e32 v119, v119
	v_mov_b32_e32 v168, v118
	v_mov_b32_e32 v169, v119
.LBB0_358:
	s_or_b64 exec, exec, s[0:1]
	s_waitcnt lgkmcnt(0)
	v_or_b32_e32 v118, 16, v144
	v_ashrrev_i32_e32 v119, 31, v118
	v_lshlrev_b64 v[118:119], 12, v[118:119]
	v_lshl_add_u64 v[118:119], s[94:95], 0, v[118:119]
	v_lshl_add_u64 v[124:125], v[142:143], 1, v[118:119]
	global_load_dwordx4 v[118:121], v[124:125], off
	s_waitcnt vmcnt(0)
	v_lshlrev_b32_e32 v117, 16, v118
	v_and_b32_e32 v118, 0xffff0000, v118
	v_lshlrev_b32_e32 v123, 16, v119
	v_and_b32_e32 v119, 0xffff0000, v119
	v_lshlrev_b32_e32 v126, 16, v120
	v_and_b32_e32 v120, 0xffff0000, v120
	v_lshlrev_b32_e32 v127, 16, v121
	v_and_b32_e32 v121, 0xffff0000, v121
	v_fmac_f32_e32 v117, 0.5, v110
	v_fmac_f32_e32 v118, 0.5, v111
	v_fmac_f32_e32 v123, 0.5, v112
	v_fmac_f32_e32 v119, 0.5, v113
	v_fmac_f32_e32 v126, 0.5, v106
	v_fmac_f32_e32 v120, 0.5, v107
	v_fmac_f32_e32 v127, 0.5, v108
	v_fmac_f32_e32 v121, 0.5, v109
	v_cvt_pk_bf16_f32 v106, v117, v118
	v_cvt_pk_bf16_f32 v107, v123, v119
	v_cvt_pk_bf16_f32 v108, v126, v120
	v_cvt_pk_bf16_f32 v109, v127, v121
	global_load_dwordx4 v[110:113], v[124:125], off offset:256
	v_lshlrev_b32_e32 v117, 16, v106
	global_store_dwordx4 v[124:125], v[106:109], off
	v_lshlrev_b32_e32 v118, 16, v107
	v_lshlrev_b32_e32 v119, 16, v108
	v_and_b32_e32 v106, 0xffff0000, v106
	v_and_b32_e32 v107, 0xffff0000, v107
	v_and_b32_e32 v108, 0xffff0000, v108
	v_lshlrev_b32_e32 v120, 16, v109
	v_and_b32_e32 v109, 0xffff0000, v109
	v_mul_f32_e32 v106, v106, v106
	v_mul_f32_e32 v107, v107, v107
	v_mul_f32_e32 v108, v108, v108
	v_mul_f32_e32 v109, v109, v109
	v_fmac_f32_e32 v106, v117, v117
	v_fmac_f32_e32 v107, v118, v118
	v_fmac_f32_e32 v108, v119, v119
	v_fmac_f32_e32 v109, v120, v120
	v_add_f32_e32 v106, v106, v107
	v_add_f32_e32 v107, v108, v109
	v_add_f32_e32 v106, v106, v107
	s_waitcnt vmcnt(1)
	v_lshlrev_b32_e32 v107, 16, v110
	v_and_b32_e32 v108, 0xffff0000, v110
	v_and_b32_e32 v110, 0xffff0000, v111
	v_lshlrev_b32_e32 v109, 16, v111
	v_lshlrev_b32_e32 v111, 16, v112
	v_and_b32_e32 v112, 0xffff0000, v112
	v_lshlrev_b32_e32 v117, 16, v113
	v_and_b32_e32 v113, 0xffff0000, v113
	v_fmac_f32_e32 v108, 0.5, v103
	v_fmac_f32_e32 v110, 0.5, v105
	v_fmac_f32_e32 v107, 0.5, v102
	v_fmac_f32_e32 v109, 0.5, v104
	v_fmac_f32_e32 v111, 0.5, v98
	v_fmac_f32_e32 v112, 0.5, v99
	v_fmac_f32_e32 v117, 0.5, v100
	v_fmac_f32_e32 v113, 0.5, v101
	v_cvt_pk_bf16_f32 v100, v107, v108
	v_cvt_pk_bf16_f32 v101, v109, v110
	v_cvt_pk_bf16_f32 v102, v111, v112
	v_cvt_pk_bf16_f32 v103, v117, v113
	global_store_dwordx4 v[124:125], v[100:103], off offset:256
	v_and_b32_e32 v99, 0xffff0000, v100
	v_and_b32_e32 v105, 0xffff0000, v101
	v_and_b32_e32 v108, 0xffff0000, v102
	v_and_b32_e32 v110, 0xffff0000, v103
	v_lshlrev_b32_e32 v98, 16, v100
	v_lshlrev_b32_e32 v104, 16, v101
	v_lshlrev_b32_e32 v107, 16, v102
	v_lshlrev_b32_e32 v109, 16, v103
	v_mul_f32_e32 v99, v99, v99
	v_mul_f32_e32 v105, v105, v105
	v_mul_f32_e32 v108, v108, v108
	v_mul_f32_e32 v110, v110, v110
	v_fmac_f32_e32 v99, v98, v98
	v_fmac_f32_e32 v105, v104, v104
	v_fmac_f32_e32 v108, v107, v107
	v_fmac_f32_e32 v110, v109, v109
	v_add_f32_e32 v98, v99, v105
	v_add_f32_e32 v99, v108, v110
	v_add_f32_e32 v98, v98, v99
	v_add_f32_e32 v98, v106, v98
	ds_bpermute_b32 v99, v122, v98
	s_waitcnt lgkmcnt(0)
	v_add_f32_e32 v98, v98, v99
	ds_bpermute_b32 v99, v116, v98
	s_and_saveexec_b64 s[0:1], s[40:41]
	s_cbranch_execz .LBB0_360
	s_waitcnt lgkmcnt(0)
	v_add_f32_e32 v98, v98, v99
	v_fma_f32 v98, v98, s6, 0.5
	v_trunc_f32_e32 v98, v98
	v_mul_f32_e32 v99, 0x2f800000, v98
	v_floor_f32_e32 v99, v99
	v_fmac_f32_e32 v98, 0xcf800000, v99
	v_cvt_u32_f32_e32 v98, v98
	v_cvt_u32_f32_e32 v99, v99
	v_mov_b32_e32 v170, v98
	v_mov_b32_e32 v171, v99
.LBB0_360:
	s_or_b64 exec, exec, s[0:1]
	v_or_b32_e32 v98, 32, v144
	s_waitcnt lgkmcnt(0)
	v_ashrrev_i32_e32 v99, 31, v98
	v_lshlrev_b64 v[98:99], 12, v[98:99]
	v_lshl_add_u64 v[98:99], s[94:95], 0, v[98:99]
	v_lshl_add_u64 v[102:103], v[142:143], 1, v[98:99]
	global_load_dwordx4 v[98:101], v[102:103], off
	s_waitcnt vmcnt(0)
	v_lshlrev_b32_e32 v104, 16, v98
	v_and_b32_e32 v98, 0xffff0000, v98
	v_lshlrev_b32_e32 v105, 16, v99
	v_and_b32_e32 v99, 0xffff0000, v99
	v_lshlrev_b32_e32 v106, 16, v100
	v_and_b32_e32 v100, 0xffff0000, v100
	v_lshlrev_b32_e32 v107, 16, v101
	v_and_b32_e32 v101, 0xffff0000, v101
	v_fmac_f32_e32 v104, 0.5, v94
	v_fmac_f32_e32 v98, 0.5, v95
	v_fmac_f32_e32 v105, 0.5, v96
	v_fmac_f32_e32 v99, 0.5, v97
	v_fmac_f32_e32 v106, 0.5, v90
	v_fmac_f32_e32 v100, 0.5, v91
	v_fmac_f32_e32 v107, 0.5, v92
	v_fmac_f32_e32 v101, 0.5, v93
	v_cvt_pk_bf16_f32 v90, v104, v98
	v_cvt_pk_bf16_f32 v91, v105, v99
	v_cvt_pk_bf16_f32 v92, v106, v100
	v_cvt_pk_bf16_f32 v93, v107, v101
	global_load_dwordx4 v[94:97], v[102:103], off offset:256
	v_lshlrev_b32_e32 v98, 16, v90
	global_store_dwordx4 v[102:103], v[90:93], off
	v_lshlrev_b32_e32 v99, 16, v91
	v_lshlrev_b32_e32 v100, 16, v92
	v_and_b32_e32 v90, 0xffff0000, v90
	v_and_b32_e32 v91, 0xffff0000, v91
	v_and_b32_e32 v92, 0xffff0000, v92
	v_lshlrev_b32_e32 v101, 16, v93
	v_and_b32_e32 v93, 0xffff0000, v93
	v_mul_f32_e32 v90, v90, v90
	v_mul_f32_e32 v91, v91, v91
	v_mul_f32_e32 v92, v92, v92
	v_mul_f32_e32 v93, v93, v93
	v_fmac_f32_e32 v90, v98, v98
	v_fmac_f32_e32 v91, v99, v99
	v_fmac_f32_e32 v92, v100, v100
	v_fmac_f32_e32 v93, v101, v101
	v_add_f32_e32 v90, v90, v91
	v_add_f32_e32 v91, v92, v93
	v_add_f32_e32 v90, v90, v91
	s_waitcnt vmcnt(1)
	v_lshlrev_b32_e32 v91, 16, v94
	v_and_b32_e32 v92, 0xffff0000, v94
	v_and_b32_e32 v94, 0xffff0000, v95
	v_lshlrev_b32_e32 v93, 16, v95
	v_lshlrev_b32_e32 v95, 16, v96
	v_and_b32_e32 v96, 0xffff0000, v96
	v_lshlrev_b32_e32 v98, 16, v97
	v_and_b32_e32 v97, 0xffff0000, v97
	v_fmac_f32_e32 v92, 0.5, v87
	v_fmac_f32_e32 v94, 0.5, v89
	v_fmac_f32_e32 v91, 0.5, v86
	v_fmac_f32_e32 v93, 0.5, v88
	v_fmac_f32_e32 v95, 0.5, v82
	v_fmac_f32_e32 v96, 0.5, v83
	v_fmac_f32_e32 v98, 0.5, v84
	v_fmac_f32_e32 v97, 0.5, v85
	v_cvt_pk_bf16_f32 v84, v91, v92
	v_cvt_pk_bf16_f32 v85, v93, v94
	v_cvt_pk_bf16_f32 v86, v95, v96
	v_cvt_pk_bf16_f32 v87, v98, v97
	global_store_dwordx4 v[102:103], v[84:87], off offset:256
	v_and_b32_e32 v83, 0xffff0000, v84
	v_and_b32_e32 v89, 0xffff0000, v85
	v_and_b32_e32 v92, 0xffff0000, v86
	v_and_b32_e32 v94, 0xffff0000, v87
	v_lshlrev_b32_e32 v82, 16, v84
	v_lshlrev_b32_e32 v88, 16, v85
	v_lshlrev_b32_e32 v91, 16, v86
	v_lshlrev_b32_e32 v93, 16, v87
	v_mul_f32_e32 v83, v83, v83
	v_mul_f32_e32 v89, v89, v89
	v_mul_f32_e32 v92, v92, v92
	v_mul_f32_e32 v94, v94, v94
	v_fmac_f32_e32 v83, v82, v82
	v_fmac_f32_e32 v89, v88, v88
	v_fmac_f32_e32 v92, v91, v91
	v_fmac_f32_e32 v94, v93, v93
	v_add_f32_e32 v82, v83, v89
	v_add_f32_e32 v83, v92, v94
	v_add_f32_e32 v82, v82, v83
	v_add_f32_e32 v82, v90, v82
	ds_bpermute_b32 v83, v122, v82
	s_waitcnt lgkmcnt(0)
	v_add_f32_e32 v82, v82, v83
	ds_bpermute_b32 v83, v116, v82
	s_and_saveexec_b64 s[0:1], s[40:41]
	s_cbranch_execz .LBB0_362
	s_waitcnt lgkmcnt(0)
	v_add_f32_e32 v82, v82, v83
	v_fma_f32 v82, v82, s6, 0.5
	v_trunc_f32_e32 v82, v82
	v_mul_f32_e32 v83, 0x2f800000, v82
	v_floor_f32_e32 v83, v83
	v_fmac_f32_e32 v82, 0xcf800000, v83
	v_cvt_u32_f32_e32 v82, v82
	v_cvt_u32_f32_e32 v83, v83
	v_mov_b32_e32 v172, v82
	v_mov_b32_e32 v173, v83
.LBB0_362:
	s_or_b64 exec, exec, s[0:1]
	v_or_b32_e32 v82, 48, v144
	s_waitcnt lgkmcnt(0)
	v_ashrrev_i32_e32 v83, 31, v82
	v_lshlrev_b64 v[82:83], 12, v[82:83]
	v_lshl_add_u64 v[82:83], s[94:95], 0, v[82:83]
	v_lshl_add_u64 v[86:87], v[142:143], 1, v[82:83]
	global_load_dwordx4 v[82:85], v[86:87], off
	s_waitcnt vmcnt(0)
	v_lshlrev_b32_e32 v88, 16, v82
	v_and_b32_e32 v82, 0xffff0000, v82
	v_lshlrev_b32_e32 v89, 16, v83
	v_and_b32_e32 v83, 0xffff0000, v83
	v_lshlrev_b32_e32 v90, 16, v84
	v_and_b32_e32 v84, 0xffff0000, v84
	v_lshlrev_b32_e32 v91, 16, v85
	v_and_b32_e32 v85, 0xffff0000, v85
	v_fmac_f32_e32 v88, 0.5, v78
	v_fmac_f32_e32 v82, 0.5, v79
	v_fmac_f32_e32 v89, 0.5, v80
	v_fmac_f32_e32 v83, 0.5, v81
	v_fmac_f32_e32 v90, 0.5, v74
	v_fmac_f32_e32 v84, 0.5, v75
	v_fmac_f32_e32 v91, 0.5, v76
	v_fmac_f32_e32 v85, 0.5, v77
	v_cvt_pk_bf16_f32 v74, v88, v82
	v_cvt_pk_bf16_f32 v75, v89, v83
	v_cvt_pk_bf16_f32 v76, v90, v84
	v_cvt_pk_bf16_f32 v77, v91, v85
	global_load_dwordx4 v[78:81], v[86:87], off offset:256
	v_lshlrev_b32_e32 v82, 16, v74
	global_store_dwordx4 v[86:87], v[74:77], off
	v_lshlrev_b32_e32 v83, 16, v75
	v_lshlrev_b32_e32 v84, 16, v76
	v_and_b32_e32 v74, 0xffff0000, v74
	v_and_b32_e32 v75, 0xffff0000, v75
	v_and_b32_e32 v76, 0xffff0000, v76
	v_lshlrev_b32_e32 v85, 16, v77
	v_and_b32_e32 v77, 0xffff0000, v77
	v_mul_f32_e32 v74, v74, v74
	v_mul_f32_e32 v75, v75, v75
	v_mul_f32_e32 v76, v76, v76
	v_mul_f32_e32 v77, v77, v77
	v_fmac_f32_e32 v74, v82, v82
	v_fmac_f32_e32 v75, v83, v83
	v_fmac_f32_e32 v76, v84, v84
	v_fmac_f32_e32 v77, v85, v85
	v_add_f32_e32 v74, v74, v75
	v_add_f32_e32 v75, v76, v77
	v_add_f32_e32 v74, v74, v75
	s_waitcnt vmcnt(1)
	v_lshlrev_b32_e32 v75, 16, v78
	v_and_b32_e32 v76, 0xffff0000, v78
	v_and_b32_e32 v78, 0xffff0000, v79
	v_lshlrev_b32_e32 v77, 16, v79
	v_lshlrev_b32_e32 v79, 16, v80
	v_and_b32_e32 v80, 0xffff0000, v80
	v_lshlrev_b32_e32 v82, 16, v81
	v_and_b32_e32 v81, 0xffff0000, v81
	v_fmac_f32_e32 v76, 0.5, v71
	v_fmac_f32_e32 v78, 0.5, v73
	v_fmac_f32_e32 v75, 0.5, v70
	v_fmac_f32_e32 v77, 0.5, v72
	v_fmac_f32_e32 v79, 0.5, v66
	v_fmac_f32_e32 v80, 0.5, v67
	v_fmac_f32_e32 v82, 0.5, v68
	v_fmac_f32_e32 v81, 0.5, v69
	v_cvt_pk_bf16_f32 v68, v75, v76
	v_cvt_pk_bf16_f32 v69, v77, v78
	v_cvt_pk_bf16_f32 v70, v79, v80
	v_cvt_pk_bf16_f32 v71, v82, v81
	global_store_dwordx4 v[86:87], v[68:71], off offset:256
	v_and_b32_e32 v67, 0xffff0000, v68
	v_and_b32_e32 v73, 0xffff0000, v69
	v_and_b32_e32 v76, 0xffff0000, v70
	v_and_b32_e32 v78, 0xffff0000, v71
	v_lshlrev_b32_e32 v66, 16, v68
	v_lshlrev_b32_e32 v72, 16, v69
	v_lshlrev_b32_e32 v75, 16, v70
	v_lshlrev_b32_e32 v77, 16, v71
	v_mul_f32_e32 v67, v67, v67
	v_mul_f32_e32 v73, v73, v73
	v_mul_f32_e32 v76, v76, v76
	v_mul_f32_e32 v78, v78, v78
	v_fmac_f32_e32 v67, v66, v66
	v_fmac_f32_e32 v73, v72, v72
	v_fmac_f32_e32 v76, v75, v75
	v_fmac_f32_e32 v78, v77, v77
	v_add_f32_e32 v66, v67, v73
	v_add_f32_e32 v67, v76, v78
	v_add_f32_e32 v66, v66, v67
	v_add_f32_e32 v66, v74, v66
	ds_bpermute_b32 v67, v122, v66
	s_waitcnt lgkmcnt(0)
	v_add_f32_e32 v66, v66, v67
	ds_bpermute_b32 v67, v116, v66
	s_and_saveexec_b64 s[0:1], s[40:41]
	s_cbranch_execz .LBB0_364
	s_waitcnt lgkmcnt(0)
	v_add_f32_e32 v66, v66, v67
	v_fma_f32 v66, v66, s6, 0.5
	v_trunc_f32_e32 v66, v66
	v_mul_f32_e32 v67, 0x2f800000, v66
	v_floor_f32_e32 v67, v67
	v_fmac_f32_e32 v66, 0xcf800000, v67
	v_cvt_u32_f32_e32 v66, v66
	v_cvt_u32_f32_e32 v67, v67
	v_mov_b32_e32 v174, v66
	v_mov_b32_e32 v175, v67
.LBB0_364:
	s_or_b64 exec, exec, s[0:1]
	v_add_co_u32_e32 v70, vcc, 0x80000, v140
	s_mov_b64 s[0:1], 0x80000
	s_nop 0
	v_addc_co_u32_e32 v71, vcc, 0, v141, vcc
	s_waitcnt lgkmcnt(0)
	global_load_dwordx4 v[66:69], v[70:71], off
	v_lshl_add_u64 v[72:73], v[140:141], 0, s[0:1]
	s_waitcnt vmcnt(0)
	v_lshlrev_b32_e32 v74, 16, v66
	v_and_b32_e32 v66, 0xffff0000, v66
	v_lshlrev_b32_e32 v75, 16, v67
	v_and_b32_e32 v67, 0xffff0000, v67
	v_lshlrev_b32_e32 v76, 16, v68
	v_and_b32_e32 v68, 0xffff0000, v68
	v_lshlrev_b32_e32 v77, 16, v69
	v_and_b32_e32 v69, 0xffff0000, v69
	v_fmac_f32_e32 v74, 0.5, v62
	v_fmac_f32_e32 v66, 0.5, v63
	v_fmac_f32_e32 v75, 0.5, v64
	v_fmac_f32_e32 v67, 0.5, v65
	v_fmac_f32_e32 v76, 0.5, v58
	v_fmac_f32_e32 v68, 0.5, v59
	v_fmac_f32_e32 v77, 0.5, v60
	v_fmac_f32_e32 v69, 0.5, v61
	v_cvt_pk_bf16_f32 v58, v74, v66
	v_cvt_pk_bf16_f32 v59, v75, v67
	v_cvt_pk_bf16_f32 v60, v76, v68
	v_cvt_pk_bf16_f32 v61, v77, v69
	global_load_dwordx4 v[62:65], v[72:73], off offset:256
	v_lshlrev_b32_e32 v66, 16, v58
	global_store_dwordx4 v[70:71], v[58:61], off
	v_lshlrev_b32_e32 v67, 16, v59
	v_lshlrev_b32_e32 v68, 16, v60
	v_and_b32_e32 v58, 0xffff0000, v58
	v_and_b32_e32 v59, 0xffff0000, v59
	v_and_b32_e32 v60, 0xffff0000, v60
	v_lshlrev_b32_e32 v69, 16, v61
	v_and_b32_e32 v61, 0xffff0000, v61
	v_mul_f32_e32 v58, v58, v58
	v_mul_f32_e32 v59, v59, v59
	v_mul_f32_e32 v60, v60, v60
	v_mul_f32_e32 v61, v61, v61
	v_fmac_f32_e32 v58, v66, v66
	v_fmac_f32_e32 v59, v67, v67
	v_fmac_f32_e32 v60, v68, v68
	v_fmac_f32_e32 v61, v69, v69
	v_add_f32_e32 v58, v58, v59
	v_add_f32_e32 v59, v60, v61
	v_add_f32_e32 v58, v58, v59
	s_waitcnt vmcnt(1)
	v_lshlrev_b32_e32 v59, 16, v62
	v_and_b32_e32 v60, 0xffff0000, v62
	v_and_b32_e32 v62, 0xffff0000, v63
	v_lshlrev_b32_e32 v61, 16, v63
	v_lshlrev_b32_e32 v63, 16, v64
	v_and_b32_e32 v64, 0xffff0000, v64
	v_lshlrev_b32_e32 v66, 16, v65
	v_and_b32_e32 v65, 0xffff0000, v65
	v_fmac_f32_e32 v60, 0.5, v55
	v_fmac_f32_e32 v62, 0.5, v57
	v_fmac_f32_e32 v59, 0.5, v54
	v_fmac_f32_e32 v61, 0.5, v56
	v_fmac_f32_e32 v63, 0.5, v50
	v_fmac_f32_e32 v64, 0.5, v51
	v_fmac_f32_e32 v66, 0.5, v52
	v_fmac_f32_e32 v65, 0.5, v53
	v_cvt_pk_bf16_f32 v52, v59, v60
	v_cvt_pk_bf16_f32 v53, v61, v62
	v_cvt_pk_bf16_f32 v54, v63, v64
	v_cvt_pk_bf16_f32 v55, v66, v65
	global_store_dwordx4 v[72:73], v[52:55], off offset:256
	v_and_b32_e32 v51, 0xffff0000, v52
	v_and_b32_e32 v57, 0xffff0000, v53
	v_and_b32_e32 v60, 0xffff0000, v54
	v_and_b32_e32 v62, 0xffff0000, v55
	v_lshlrev_b32_e32 v50, 16, v52
	v_lshlrev_b32_e32 v56, 16, v53
	v_lshlrev_b32_e32 v59, 16, v54
	v_lshlrev_b32_e32 v61, 16, v55
	v_mul_f32_e32 v51, v51, v51
	v_mul_f32_e32 v57, v57, v57
	v_mul_f32_e32 v60, v60, v60
	v_mul_f32_e32 v62, v62, v62
	v_fmac_f32_e32 v51, v50, v50
	v_fmac_f32_e32 v57, v56, v56
	v_fmac_f32_e32 v60, v59, v59
	v_fmac_f32_e32 v62, v61, v61
	v_add_f32_e32 v50, v51, v57
	v_add_f32_e32 v51, v60, v62
	v_add_f32_e32 v50, v50, v51
	v_add_f32_e32 v50, v58, v50
	ds_bpermute_b32 v51, v122, v50
	s_waitcnt lgkmcnt(0)
	v_add_f32_e32 v50, v50, v51
	ds_bpermute_b32 v51, v116, v50
	s_and_saveexec_b64 s[0:1], s[40:41]
	s_cbranch_execz .LBB0_366
	s_waitcnt lgkmcnt(0)
	v_add_f32_e32 v50, v50, v51
	v_fma_f32 v50, v50, s6, 0.5
	v_trunc_f32_e32 v50, v50
	v_mul_f32_e32 v51, 0x2f800000, v50
	v_floor_f32_e32 v51, v51
	v_fmac_f32_e32 v50, 0xcf800000, v51
	v_cvt_u32_f32_e32 v50, v50
	v_cvt_u32_f32_e32 v51, v51
	v_mov_b32_e32 v176, v50
	v_mov_b32_e32 v177, v51
.LBB0_366:
	s_or_b64 exec, exec, s[0:1]
	v_add_co_u32_e32 v56, vcc, 0x90000, v140
	s_mov_b64 s[0:1], 0x90000
	s_nop 0
	v_addc_co_u32_e32 v57, vcc, 0, v141, vcc
	global_load_dwordx4 v[52:55], v[56:57], off
	s_waitcnt lgkmcnt(0)
	v_lshl_add_u64 v[50:51], v[140:141], 0, s[0:1]
	s_waitcnt vmcnt(0)
	v_lshlrev_b32_e32 v58, 16, v52
	v_fmac_f32_e32 v58, 0.5, v46
	v_and_b32_e32 v46, 0xffff0000, v52
	v_fmac_f32_e32 v46, 0.5, v47
	v_lshlrev_b32_e32 v47, 16, v53
	v_fmac_f32_e32 v47, 0.5, v48
	v_and_b32_e32 v48, 0xffff0000, v53
	v_fmac_f32_e32 v48, 0.5, v49
	v_cvt_pk_bf16_f32 v46, v58, v46
	v_cvt_pk_bf16_f32 v47, v47, v48
	v_lshlrev_b32_e32 v48, 16, v54
	v_fmac_f32_e32 v48, 0.5, v42
	v_and_b32_e32 v42, 0xffff0000, v54
	v_fmac_f32_e32 v42, 0.5, v43
	v_and_b32_e32 v43, 0xffff0000, v55
	v_cvt_pk_bf16_f32 v48, v48, v42
	v_lshlrev_b32_e32 v42, 16, v55
	v_fmac_f32_e32 v43, 0.5, v45
	v_fmac_f32_e32 v42, 0.5, v44
	v_cvt_pk_bf16_f32 v49, v42, v43
	v_and_b32_e32 v43, 0xffff0000, v46
	v_lshlrev_b32_e32 v42, 16, v46
	v_and_b32_e32 v45, 0xffff0000, v47
	v_mul_f32_e32 v43, v43, v43
	v_lshlrev_b32_e32 v44, 16, v47
	v_fmac_f32_e32 v43, v42, v42
	v_mul_f32_e32 v42, v45, v45
	global_store_dwordx4 v[56:57], v[46:49], off
	v_fmac_f32_e32 v42, v44, v44
	v_add_f32_e32 v42, v43, v42
	v_lshlrev_b32_e32 v46, 16, v48
	v_and_b32_e32 v47, 0xffff0000, v48
	v_lshlrev_b32_e32 v48, 16, v49
	v_and_b32_e32 v49, 0xffff0000, v49
	v_mul_f32_e32 v43, v47, v47
	v_mul_f32_e32 v44, v49, v49
	v_fmac_f32_e32 v43, v46, v46
	v_fmac_f32_e32 v44, v48, v48
	v_add_f32_e32 v43, v43, v44
	v_add_f32_e32 v46, v42, v43
	global_load_dwordx4 v[42:45], v[50:51], off offset:256
	s_waitcnt vmcnt(0)
	v_lshlrev_b32_e32 v47, 16, v42
	v_fmac_f32_e32 v47, 0.5, v38
	v_and_b32_e32 v38, 0xffff0000, v42
	v_fmac_f32_e32 v38, 0.5, v39
	v_lshlrev_b32_e32 v39, 16, v43
	v_fmac_f32_e32 v39, 0.5, v40
	v_and_b32_e32 v40, 0xffff0000, v43
	v_fmac_f32_e32 v40, 0.5, v41
	v_cvt_pk_bf16_f32 v38, v47, v38
	v_cvt_pk_bf16_f32 v39, v39, v40
	v_lshlrev_b32_e32 v40, 16, v44
	v_fmac_f32_e32 v40, 0.5, v34
	v_and_b32_e32 v34, 0xffff0000, v44
	v_fmac_f32_e32 v34, 0.5, v35
	v_and_b32_e32 v35, 0xffff0000, v45
	v_cvt_pk_bf16_f32 v40, v40, v34
	v_lshlrev_b32_e32 v34, 16, v45
	v_fmac_f32_e32 v35, 0.5, v37
	v_fmac_f32_e32 v34, 0.5, v36
	v_cvt_pk_bf16_f32 v41, v34, v35
	v_and_b32_e32 v35, 0xffff0000, v38
	v_lshlrev_b32_e32 v34, 16, v38
	v_and_b32_e32 v37, 0xffff0000, v39
	v_mul_f32_e32 v35, v35, v35
	v_lshlrev_b32_e32 v36, 16, v39
	v_fmac_f32_e32 v35, v34, v34
	v_mul_f32_e32 v34, v37, v37
	global_store_dwordx4 v[50:51], v[38:41], off offset:256
	v_fmac_f32_e32 v34, v36, v36
	v_add_f32_e32 v34, v35, v34
	v_lshlrev_b32_e32 v38, 16, v40
	v_and_b32_e32 v39, 0xffff0000, v40
	v_lshlrev_b32_e32 v40, 16, v41
	v_and_b32_e32 v41, 0xffff0000, v41
	v_mul_f32_e32 v35, v39, v39
	v_mul_f32_e32 v36, v41, v41
	v_fmac_f32_e32 v35, v38, v38
	v_fmac_f32_e32 v36, v40, v40
	v_add_f32_e32 v35, v35, v36
	v_add_f32_e32 v34, v34, v35
	v_add_f32_e32 v34, v46, v34
	ds_bpermute_b32 v35, v122, v34
	s_waitcnt lgkmcnt(0)
	v_add_f32_e32 v34, v34, v35
	ds_bpermute_b32 v35, v116, v34
	s_and_saveexec_b64 s[0:1], s[40:41]
	s_cbranch_execz .LBB0_368
	s_waitcnt lgkmcnt(0)
	v_add_f32_e32 v34, v34, v35
	v_fma_f32 v34, v34, s6, 0.5
	v_trunc_f32_e32 v34, v34
	v_mul_f32_e32 v35, 0x2f800000, v34
	v_floor_f32_e32 v35, v35
	v_fmac_f32_e32 v34, 0xcf800000, v35
	v_cvt_u32_f32_e32 v34, v34
	v_cvt_u32_f32_e32 v35, v35
	v_mov_b32_e32 v178, v34
	v_mov_b32_e32 v179, v35
.LBB0_368:
	s_or_b64 exec, exec, s[0:1]
	v_add_co_u32_e32 v40, vcc, 0xa0000, v140
	s_mov_b64 s[0:1], 0xa0000
	s_nop 0
	v_addc_co_u32_e32 v41, vcc, 0, v141, vcc
	global_load_dwordx4 v[36:39], v[40:41], off
	s_waitcnt lgkmcnt(0)
	v_lshl_add_u64 v[34:35], v[140:141], 0, s[0:1]
	s_waitcnt vmcnt(0)
	v_lshlrev_b32_e32 v42, 16, v36
	v_fmac_f32_e32 v42, 0.5, v30
	v_and_b32_e32 v30, 0xffff0000, v36
	v_fmac_f32_e32 v30, 0.5, v31
	v_lshlrev_b32_e32 v31, 16, v37
	v_fmac_f32_e32 v31, 0.5, v32
	v_and_b32_e32 v32, 0xffff0000, v37
	v_fmac_f32_e32 v32, 0.5, v33
	v_cvt_pk_bf16_f32 v30, v42, v30
	v_cvt_pk_bf16_f32 v31, v31, v32
	v_lshlrev_b32_e32 v32, 16, v38
	v_fmac_f32_e32 v32, 0.5, v26
	v_and_b32_e32 v26, 0xffff0000, v38
	v_fmac_f32_e32 v26, 0.5, v27
	v_and_b32_e32 v27, 0xffff0000, v39
	v_cvt_pk_bf16_f32 v32, v32, v26
	v_lshlrev_b32_e32 v26, 16, v39
	v_fmac_f32_e32 v27, 0.5, v29
	v_fmac_f32_e32 v26, 0.5, v28
	v_cvt_pk_bf16_f32 v33, v26, v27
	v_and_b32_e32 v27, 0xffff0000, v30
	v_lshlrev_b32_e32 v26, 16, v30
	v_and_b32_e32 v29, 0xffff0000, v31
	v_mul_f32_e32 v27, v27, v27
	v_lshlrev_b32_e32 v28, 16, v31
	v_fmac_f32_e32 v27, v26, v26
	v_mul_f32_e32 v26, v29, v29
	global_store_dwordx4 v[40:41], v[30:33], off
	v_fmac_f32_e32 v26, v28, v28
	v_add_f32_e32 v26, v27, v26
	v_lshlrev_b32_e32 v30, 16, v32
	v_and_b32_e32 v31, 0xffff0000, v32
	v_lshlrev_b32_e32 v32, 16, v33
	v_and_b32_e32 v33, 0xffff0000, v33
	v_mul_f32_e32 v27, v31, v31
	v_mul_f32_e32 v28, v33, v33
	v_fmac_f32_e32 v27, v30, v30
	v_fmac_f32_e32 v28, v32, v32
	v_add_f32_e32 v27, v27, v28
	v_add_f32_e32 v30, v26, v27
	global_load_dwordx4 v[26:29], v[34:35], off offset:256
	s_waitcnt vmcnt(0)
	v_lshlrev_b32_e32 v31, 16, v26
	v_fmac_f32_e32 v31, 0.5, v22
	v_and_b32_e32 v22, 0xffff0000, v26
	v_fmac_f32_e32 v22, 0.5, v23
	v_lshlrev_b32_e32 v23, 16, v27
	v_fmac_f32_e32 v23, 0.5, v24
	v_and_b32_e32 v24, 0xffff0000, v27
	v_fmac_f32_e32 v24, 0.5, v25
	v_cvt_pk_bf16_f32 v22, v31, v22
	v_cvt_pk_bf16_f32 v23, v23, v24
	v_lshlrev_b32_e32 v24, 16, v28
	v_fmac_f32_e32 v24, 0.5, v18
	v_and_b32_e32 v18, 0xffff0000, v28
	v_fmac_f32_e32 v18, 0.5, v19
	v_and_b32_e32 v19, 0xffff0000, v29
	v_cvt_pk_bf16_f32 v24, v24, v18
	v_lshlrev_b32_e32 v18, 16, v29
	v_fmac_f32_e32 v19, 0.5, v21
	v_fmac_f32_e32 v18, 0.5, v20
	v_cvt_pk_bf16_f32 v25, v18, v19
	v_and_b32_e32 v19, 0xffff0000, v22
	v_lshlrev_b32_e32 v18, 16, v22
	v_and_b32_e32 v21, 0xffff0000, v23
	v_mul_f32_e32 v19, v19, v19
	v_lshlrev_b32_e32 v20, 16, v23
	v_fmac_f32_e32 v19, v18, v18
	v_mul_f32_e32 v18, v21, v21
	global_store_dwordx4 v[34:35], v[22:25], off offset:256
	v_fmac_f32_e32 v18, v20, v20
	v_add_f32_e32 v18, v19, v18
	v_lshlrev_b32_e32 v22, 16, v24
	v_and_b32_e32 v23, 0xffff0000, v24
	v_lshlrev_b32_e32 v24, 16, v25
	v_and_b32_e32 v25, 0xffff0000, v25
	v_mul_f32_e32 v19, v23, v23
	v_mul_f32_e32 v20, v25, v25
	v_fmac_f32_e32 v19, v22, v22
	v_fmac_f32_e32 v20, v24, v24
	v_add_f32_e32 v19, v19, v20
	v_add_f32_e32 v18, v18, v19
	v_add_f32_e32 v18, v30, v18
	ds_bpermute_b32 v19, v122, v18
	s_waitcnt lgkmcnt(0)
	v_add_f32_e32 v18, v18, v19
	ds_bpermute_b32 v19, v116, v18
	s_and_saveexec_b64 s[0:1], s[40:41]
	s_cbranch_execz .LBB0_370
	s_waitcnt lgkmcnt(0)
	v_add_f32_e32 v18, v18, v19
	v_fma_f32 v18, v18, s6, 0.5
	v_trunc_f32_e32 v18, v18
	v_mul_f32_e32 v19, 0x2f800000, v18
	v_floor_f32_e32 v19, v19
	v_fmac_f32_e32 v18, 0xcf800000, v19
	v_cvt_u32_f32_e32 v18, v18
	v_cvt_u32_f32_e32 v19, v19
	v_mov_b32_e32 v180, v18
	v_mov_b32_e32 v181, v19

.LBB0_372:
	s_or_b64 exec, exec, s[0:1]
	s_and_saveexec_b64 s[0:1], s[40:41]
	global_atomic_add_x2 v[114:115], v[168:169], off
	global_atomic_add_x2 v[114:115], v[170:171], off offset:128
	global_atomic_add_x2 v[114:115], v[172:173], off offset:256
	global_atomic_add_x2 v[114:115], v[174:175], off offset:384
	global_atomic_add_x2 v[114:115], v[176:177], off offset:1024
	global_atomic_add_x2 v[114:115], v[178:179], off offset:1152
	global_atomic_add_x2 v[114:115], v[180:181], off offset:1280
	s_or_b64 exec, exec, s[0:1]
	s_and_b64 vcc, exec, s[42:43]
	s_mov_b64 s[0:1], -1
	s_cbranch_vccnz .LBB0_347
	s_andn2_b64 vcc, exec, s[22:23]
	s_cbranch_vccnz .LBB0_346
	s_barrier
	s_branch .LBB0_346

.LBB0_718:
	v_lshl_add_u32 v142, s64, 8, v1
	v_ashrrev_i32_e32 v143, 31, v142
	v_lshl_or_b32 v140, s0, 7, v145
	v_lshlrev_b64 v[148:149], 12, v[142:143]
	v_ashrrev_i32_e32 v141, 31, v140
	v_lshl_add_u64 v[148:149], s[94:95], 0, v[148:149]
	v_lshl_add_u64 v[152:153], v[140:141], 1, v[148:149]
	global_load_dwordx4 v[148:151], v[152:153], off
	v_mul_f32_e32 v122, 0xbfb8aa3b, v122
	v_mul_f32_e32 v114, 0xbfb8aa3b, v114
	v_exp_f32_e32 v122, v122
	v_exp_f32_e32 v114, v114
	v_add_f32_e32 v122, 1.0, v122
	v_add_f32_e32 v114, 1.0, v114
	v_rcp_f32_e32 v122, v122
	v_rcp_f32_e32 v114, v114
	s_waitcnt vmcnt(0)
	v_lshlrev_b32_e32 v147, 16, v148
	v_lshlrev_b32_e32 v155, 16, v150
	v_fmac_f32_e32 v147, v122, v126
	v_mul_f32_e32 v122, 0xbfb8aa3b, v123
	v_fmac_f32_e32 v155, v114, v118
	v_mul_f32_e32 v114, 0xbfb8aa3b, v115
	v_exp_f32_e32 v122, v122
	v_exp_f32_e32 v114, v114
	v_and_b32_e32 v148, 0xffff0000, v148
	v_and_b32_e32 v150, 0xffff0000, v150
	v_add_f32_e32 v122, 1.0, v122
	v_add_f32_e32 v114, 1.0, v114
	v_rcp_f32_e32 v122, v122
	v_rcp_f32_e32 v114, v114
	v_lshlrev_b32_e32 v154, 16, v149
	v_lshlrev_b32_e32 v156, 16, v151
	v_fmac_f32_e32 v148, v122, v127
	v_mul_f32_e32 v122, 0xbfb8aa3b, v124
	v_fmac_f32_e32 v150, v114, v119
	v_mul_f32_e32 v114, 0xbfb8aa3b, v116
	v_exp_f32_e32 v122, v122
	v_exp_f32_e32 v114, v114
	v_and_b32_e32 v149, 0xffff0000, v149
	v_and_b32_e32 v151, 0xffff0000, v151
	v_add_f32_e32 v122, 1.0, v122
	v_add_f32_e32 v114, 1.0, v114
	v_rcp_f32_e32 v122, v122
	v_rcp_f32_e32 v114, v114
	v_fmac_f32_e32 v154, v122, v128
	v_mul_f32_e32 v122, 0xbfb8aa3b, v125
	v_fmac_f32_e32 v156, v114, v120
	v_mul_f32_e32 v114, 0xbfb8aa3b, v117
	v_exp_f32_e32 v122, v122
	v_exp_f32_e32 v114, v114
	v_add_f32_e32 v122, 1.0, v122
	v_add_f32_e32 v114, 1.0, v114
	v_rcp_f32_e32 v122, v122
	v_rcp_f32_e32 v114, v114
	v_fmac_f32_e32 v149, v122, v129
	v_fmac_f32_e32 v151, v114, v121
	v_cvt_pk_bf16_f32 v114, v147, v148
	v_cvt_pk_bf16_f32 v115, v154, v149
	v_cvt_pk_bf16_f32 v116, v155, v150
	v_cvt_pk_bf16_f32 v117, v156, v151
	global_store_dwordx4 v[152:153], v[114:117], off
	v_lshlrev_b32_e32 v118, 16, v114
	v_lshlrev_b32_e32 v119, 16, v115
	v_and_b32_e32 v114, 0xffff0000, v114
	v_and_b32_e32 v115, 0xffff0000, v115
	v_mul_f32_e32 v114, v114, v114
	v_mul_f32_e32 v115, v115, v115
	v_lshlrev_b32_e32 v120, 16, v116
	v_and_b32_e32 v116, 0xffff0000, v116
	v_lshlrev_b32_e32 v121, 16, v117
	v_and_b32_e32 v117, 0xffff0000, v117
	v_fmac_f32_e32 v114, v118, v118
	v_fmac_f32_e32 v115, v119, v119
	v_add_f32_e32 v114, v114, v115
	v_mul_f32_e32 v115, v116, v116
	v_mul_f32_e32 v116, v117, v117
	v_fmac_f32_e32 v115, v120, v120
	v_fmac_f32_e32 v116, v121, v121
	v_add_f32_e32 v115, v115, v116
	v_and_b32_e32 v116, 64, v212
	v_add_f32_e32 v114, v114, v115
	v_xor_b32_e32 v115, 16, v212
	v_add_u32_e32 v117, 64, v116
	v_cmp_lt_i32_e32 vcc, v115, v117
	s_nop 1
	v_cndmask_b32_e32 v115, v212, v115, vcc
	v_lshlrev_b32_e32 v116, 2, v115
	ds_bpermute_b32 v115, v116, v114
	s_waitcnt lgkmcnt(0)
	v_add_f32_e32 v114, v114, v115
	v_xor_b32_e32 v115, 32, v212
	v_cmp_lt_i32_e32 vcc, v115, v117
	s_nop 1
	v_cndmask_b32_e32 v115, v212, v115, vcc
	v_lshlrev_b32_e32 v117, 2, v115
	ds_bpermute_b32 v115, v117, v114
	s_and_saveexec_b64 s[0:1], s[36:37]
	s_cbranch_execz .LBB0_720
	s_waitcnt lgkmcnt(0)
	v_add_f32_e32 v114, v114, v115
	v_fma_f32 v114, v114, s6, 0.5
	v_trunc_f32_e32 v114, v114
	v_mul_f32_e32 v115, 0x2f800000, v114
	v_floor_f32_e32 v115, v115
	v_fmac_f32_e32 v114, 0xcf800000, v115
	v_cvt_u32_f32_e32 v114, v114
	v_cvt_u32_f32_e32 v115, v115
	v_lshl_add_u64 v[168:169], v[142:143], 3, s[20:21]
	v_mov_b32_e32 v170, v114
	v_mov_b32_e32 v171, v115
.LBB0_720:
	s_or_b64 exec, exec, s[0:1]
	v_or_b32_e32 v114, 16, v142
	s_waitcnt lgkmcnt(0)
	v_ashrrev_i32_e32 v115, 31, v114
	v_lshlrev_b64 v[118:119], 12, v[114:115]
	v_lshl_add_u64 v[118:119], s[94:95], 0, v[118:119]
	v_lshl_add_u64 v[122:123], v[140:141], 1, v[118:119]
	global_load_dwordx4 v[118:121], v[122:123], off
	v_mul_f32_e32 v110, 0xbfb8aa3b, v110
	v_mul_f32_e32 v111, 0xbfb8aa3b, v111
	v_mul_f32_e32 v112, 0xbfb8aa3b, v112
	v_mul_f32_e32 v113, 0xbfb8aa3b, v113
	v_mul_f32_e32 v102, 0xbfb8aa3b, v102
	v_mul_f32_e32 v103, 0xbfb8aa3b, v103
	v_mul_f32_e32 v104, 0xbfb8aa3b, v104
	v_mul_f32_e32 v105, 0xbfb8aa3b, v105
	v_exp_f32_e32 v110, v110
	v_exp_f32_e32 v111, v111
	v_exp_f32_e32 v112, v112
	v_exp_f32_e32 v113, v113
	v_exp_f32_e32 v102, v102
	v_exp_f32_e32 v103, v103
	v_exp_f32_e32 v104, v104
	v_exp_f32_e32 v105, v105
	v_add_f32_e32 v110, 1.0, v110
	v_add_f32_e32 v111, 1.0, v111
	v_add_f32_e32 v112, 1.0, v112
	v_add_f32_e32 v113, 1.0, v113
	v_add_f32_e32 v102, 1.0, v102
	v_add_f32_e32 v103, 1.0, v103
	v_add_f32_e32 v104, 1.0, v104
	v_add_f32_e32 v105, 1.0, v105
	v_rcp_f32_e32 v110, v110
	v_rcp_f32_e32 v111, v111
	v_rcp_f32_e32 v112, v112
	v_rcp_f32_e32 v113, v113
	v_rcp_f32_e32 v102, v102
	v_rcp_f32_e32 v103, v103
	v_rcp_f32_e32 v104, v104
	v_rcp_f32_e32 v105, v105
	s_waitcnt vmcnt(0)
	v_lshlrev_b32_e32 v124, 16, v118
	v_and_b32_e32 v118, 0xffff0000, v118
	v_lshlrev_b32_e32 v125, 16, v119
	v_and_b32_e32 v119, 0xffff0000, v119
	v_lshlrev_b32_e32 v126, 16, v120
	v_and_b32_e32 v120, 0xffff0000, v120
	v_lshlrev_b32_e32 v127, 16, v121
	v_and_b32_e32 v121, 0xffff0000, v121
	v_fmac_f32_e32 v124, v110, v106
	v_fmac_f32_e32 v118, v111, v107
	v_fmac_f32_e32 v125, v112, v108
	v_fmac_f32_e32 v119, v113, v109
	v_fmac_f32_e32 v126, v102, v98
	v_fmac_f32_e32 v120, v103, v99
	v_fmac_f32_e32 v127, v104, v100
	v_fmac_f32_e32 v121, v105, v101
	v_cvt_pk_bf16_f32 v100, v124, v118
	v_cvt_pk_bf16_f32 v101, v125, v119
	v_cvt_pk_bf16_f32 v102, v126, v120
	v_cvt_pk_bf16_f32 v103, v127, v121
	global_store_dwordx4 v[122:123], v[100:103], off
	v_and_b32_e32 v99, 0xffff0000, v100
	v_and_b32_e32 v105, 0xffff0000, v101
	v_and_b32_e32 v107, 0xffff0000, v102
	v_and_b32_e32 v109, 0xffff0000, v103
	v_lshlrev_b32_e32 v98, 16, v100
	v_lshlrev_b32_e32 v104, 16, v101
	v_lshlrev_b32_e32 v106, 16, v102
	v_lshlrev_b32_e32 v108, 16, v103
	v_mul_f32_e32 v99, v99, v99
	v_mul_f32_e32 v105, v105, v105
	v_mul_f32_e32 v107, v107, v107
	v_mul_f32_e32 v109, v109, v109
	v_fmac_f32_e32 v99, v98, v98
	v_fmac_f32_e32 v105, v104, v104
	v_fmac_f32_e32 v107, v106, v106
	v_fmac_f32_e32 v109, v108, v108
	v_add_f32_e32 v98, v99, v105
	v_add_f32_e32 v99, v107, v109
	v_add_f32_e32 v98, v98, v99
	ds_bpermute_b32 v99, v116, v98
	s_waitcnt lgkmcnt(0)
	v_add_f32_e32 v98, v98, v99
	ds_bpermute_b32 v99, v117, v98
	s_and_saveexec_b64 s[0:1], s[36:37]
	s_cbranch_execz .LBB0_722
	s_waitcnt lgkmcnt(0)
	v_add_f32_e32 v98, v98, v99
	v_fma_f32 v98, v98, s6, 0.5
	v_trunc_f32_e32 v98, v98
	v_mul_f32_e32 v99, 0x2f800000, v98
	v_floor_f32_e32 v99, v99
	v_fmac_f32_e32 v98, 0xcf800000, v99
	v_cvt_u32_f32_e32 v98, v98
	v_cvt_u32_f32_e32 v99, v99
	v_lshl_add_u64 v[172:173], v[114:115], 3, s[20:21]
	v_mov_b32_e32 v174, v98
	v_mov_b32_e32 v175, v99
.LBB0_722:
	s_or_b64 exec, exec, s[0:1]
	v_or_b32_e32 v98, 32, v142
	s_waitcnt lgkmcnt(0)
	v_ashrrev_i32_e32 v99, 31, v98
	v_lshlrev_b64 v[100:101], 12, v[98:99]
	v_lshl_add_u64 v[100:101], s[94:95], 0, v[100:101]
	v_lshl_add_u64 v[104:105], v[140:141], 1, v[100:101]
	global_load_dwordx4 v[100:103], v[104:105], off
	v_mul_f32_e32 v94, 0xbfb8aa3b, v94
	v_mul_f32_e32 v95, 0xbfb8aa3b, v95
	v_mul_f32_e32 v96, 0xbfb8aa3b, v96
	v_mul_f32_e32 v97, 0xbfb8aa3b, v97
	v_mul_f32_e32 v86, 0xbfb8aa3b, v86
	v_mul_f32_e32 v87, 0xbfb8aa3b, v87
	v_mul_f32_e32 v88, 0xbfb8aa3b, v88
	v_mul_f32_e32 v89, 0xbfb8aa3b, v89
	v_exp_f32_e32 v94, v94
	v_exp_f32_e32 v95, v95
	v_exp_f32_e32 v96, v96
	v_exp_f32_e32 v97, v97
	v_exp_f32_e32 v86, v86
	v_exp_f32_e32 v87, v87
	v_exp_f32_e32 v88, v88
	v_exp_f32_e32 v89, v89
	v_add_f32_e32 v94, 1.0, v94
	v_add_f32_e32 v95, 1.0, v95
	v_add_f32_e32 v96, 1.0, v96
	v_add_f32_e32 v97, 1.0, v97
	v_add_f32_e32 v86, 1.0, v86
	v_add_f32_e32 v87, 1.0, v87
	v_add_f32_e32 v88, 1.0, v88
	v_add_f32_e32 v89, 1.0, v89
	v_rcp_f32_e32 v94, v94
	v_rcp_f32_e32 v95, v95
	v_rcp_f32_e32 v96, v96
	v_rcp_f32_e32 v97, v97
	v_rcp_f32_e32 v86, v86
	v_rcp_f32_e32 v87, v87
	v_rcp_f32_e32 v88, v88
	v_rcp_f32_e32 v89, v89
	s_waitcnt vmcnt(0)
	v_lshlrev_b32_e32 v106, 16, v100
	v_and_b32_e32 v100, 0xffff0000, v100
	v_lshlrev_b32_e32 v107, 16, v101
	v_and_b32_e32 v101, 0xffff0000, v101
	v_lshlrev_b32_e32 v108, 16, v102
	v_and_b32_e32 v102, 0xffff0000, v102
	v_lshlrev_b32_e32 v109, 16, v103
	v_and_b32_e32 v103, 0xffff0000, v103
	v_fmac_f32_e32 v106, v94, v90
	v_fmac_f32_e32 v100, v95, v91
	v_fmac_f32_e32 v107, v96, v92
	v_fmac_f32_e32 v101, v97, v93
	v_fmac_f32_e32 v108, v86, v82
	v_fmac_f32_e32 v102, v87, v83
	v_fmac_f32_e32 v109, v88, v84
	v_fmac_f32_e32 v103, v89, v85
	v_cvt_pk_bf16_f32 v84, v106, v100
	v_cvt_pk_bf16_f32 v85, v107, v101
	v_cvt_pk_bf16_f32 v86, v108, v102
	v_cvt_pk_bf16_f32 v87, v109, v103
	global_store_dwordx4 v[104:105], v[84:87], off
	v_and_b32_e32 v83, 0xffff0000, v84
	v_and_b32_e32 v89, 0xffff0000, v85
	v_and_b32_e32 v91, 0xffff0000, v86
	v_and_b32_e32 v93, 0xffff0000, v87
	v_lshlrev_b32_e32 v82, 16, v84
	v_lshlrev_b32_e32 v88, 16, v85
	v_lshlrev_b32_e32 v90, 16, v86
	v_lshlrev_b32_e32 v92, 16, v87
	v_mul_f32_e32 v83, v83, v83
	v_mul_f32_e32 v89, v89, v89
	v_mul_f32_e32 v91, v91, v91
	v_mul_f32_e32 v93, v93, v93
	v_fmac_f32_e32 v83, v82, v82
	v_fmac_f32_e32 v89, v88, v88
	v_fmac_f32_e32 v91, v90, v90
	v_fmac_f32_e32 v93, v92, v92
	v_add_f32_e32 v82, v83, v89
	v_add_f32_e32 v83, v91, v93
	v_add_f32_e32 v82, v82, v83
	ds_bpermute_b32 v83, v116, v82
	s_waitcnt lgkmcnt(0)
	v_add_f32_e32 v82, v82, v83
	ds_bpermute_b32 v83, v117, v82
	s_and_saveexec_b64 s[0:1], s[36:37]
	s_cbranch_execz .LBB0_724
	s_waitcnt lgkmcnt(0)
	v_add_f32_e32 v82, v82, v83
	v_fma_f32 v82, v82, s6, 0.5
	v_trunc_f32_e32 v82, v82
	v_mul_f32_e32 v83, 0x2f800000, v82
	v_floor_f32_e32 v83, v83
	v_fmac_f32_e32 v82, 0xcf800000, v83
	v_cvt_u32_f32_e32 v82, v82
	v_cvt_u32_f32_e32 v83, v83
	v_lshl_add_u64 v[176:177], v[98:99], 3, s[20:21]
	v_mov_b32_e32 v178, v82
	v_mov_b32_e32 v179, v83
.LBB0_724:
	s_or_b64 exec, exec, s[0:1]
	v_or_b32_e32 v82, 48, v142
	s_waitcnt lgkmcnt(0)
	v_ashrrev_i32_e32 v83, 31, v82
	v_lshlrev_b64 v[84:85], 12, v[82:83]
	v_lshl_add_u64 v[84:85], s[94:95], 0, v[84:85]
	v_lshl_add_u64 v[88:89], v[140:141], 1, v[84:85]
	global_load_dwordx4 v[84:87], v[88:89], off
	v_mul_f32_e32 v78, 0xbfb8aa3b, v78
	v_mul_f32_e32 v79, 0xbfb8aa3b, v79
	v_mul_f32_e32 v80, 0xbfb8aa3b, v80
	v_mul_f32_e32 v81, 0xbfb8aa3b, v81
	v_mul_f32_e32 v70, 0xbfb8aa3b, v70
	v_mul_f32_e32 v71, 0xbfb8aa3b, v71
	v_mul_f32_e32 v72, 0xbfb8aa3b, v72
	v_mul_f32_e32 v73, 0xbfb8aa3b, v73
	v_exp_f32_e32 v78, v78
	v_exp_f32_e32 v79, v79
	v_exp_f32_e32 v80, v80
	v_exp_f32_e32 v81, v81
	v_exp_f32_e32 v70, v70
	v_exp_f32_e32 v71, v71
	v_exp_f32_e32 v72, v72
	v_exp_f32_e32 v73, v73
	v_add_f32_e32 v78, 1.0, v78
	v_add_f32_e32 v79, 1.0, v79
	v_add_f32_e32 v80, 1.0, v80
	v_add_f32_e32 v81, 1.0, v81
	v_add_f32_e32 v70, 1.0, v70
	v_add_f32_e32 v71, 1.0, v71
	v_add_f32_e32 v72, 1.0, v72
	v_add_f32_e32 v73, 1.0, v73
	v_rcp_f32_e32 v78, v78
	v_rcp_f32_e32 v79, v79
	v_rcp_f32_e32 v80, v80
	v_rcp_f32_e32 v81, v81
	v_rcp_f32_e32 v70, v70
	v_rcp_f32_e32 v71, v71
	v_rcp_f32_e32 v72, v72
	v_rcp_f32_e32 v73, v73
	s_waitcnt vmcnt(0)
	v_lshlrev_b32_e32 v90, 16, v84
	v_and_b32_e32 v84, 0xffff0000, v84
	v_lshlrev_b32_e32 v91, 16, v85
	v_and_b32_e32 v85, 0xffff0000, v85
	v_lshlrev_b32_e32 v92, 16, v86
	v_and_b32_e32 v86, 0xffff0000, v86
	v_lshlrev_b32_e32 v93, 16, v87
	v_and_b32_e32 v87, 0xffff0000, v87
	v_fmac_f32_e32 v90, v78, v74
	v_fmac_f32_e32 v84, v79, v75
	v_fmac_f32_e32 v91, v80, v76
	v_fmac_f32_e32 v85, v81, v77
	v_fmac_f32_e32 v92, v70, v66
	v_fmac_f32_e32 v86, v71, v67
	v_fmac_f32_e32 v93, v72, v68
	v_fmac_f32_e32 v87, v73, v69
	v_cvt_pk_bf16_f32 v68, v90, v84
	v_cvt_pk_bf16_f32 v69, v91, v85
	v_cvt_pk_bf16_f32 v70, v92, v86
	v_cvt_pk_bf16_f32 v71, v93, v87
	global_store_dwordx4 v[88:89], v[68:71], off
	v_and_b32_e32 v67, 0xffff0000, v68
	v_and_b32_e32 v73, 0xffff0000, v69
	v_and_b32_e32 v75, 0xffff0000, v70
	v_and_b32_e32 v77, 0xffff0000, v71
	v_lshlrev_b32_e32 v66, 16, v68
	v_lshlrev_b32_e32 v72, 16, v69
	v_lshlrev_b32_e32 v74, 16, v70
	v_lshlrev_b32_e32 v76, 16, v71
	v_mul_f32_e32 v67, v67, v67
	v_mul_f32_e32 v73, v73, v73
	v_mul_f32_e32 v75, v75, v75
	v_mul_f32_e32 v77, v77, v77
	v_fmac_f32_e32 v67, v66, v66
	v_fmac_f32_e32 v73, v72, v72
	v_fmac_f32_e32 v75, v74, v74
	v_fmac_f32_e32 v77, v76, v76
	v_add_f32_e32 v66, v67, v73
	v_add_f32_e32 v67, v75, v77
	v_add_f32_e32 v66, v66, v67
	ds_bpermute_b32 v67, v116, v66
	s_waitcnt lgkmcnt(0)
	v_add_f32_e32 v66, v66, v67
	ds_bpermute_b32 v67, v117, v66
	s_and_saveexec_b64 s[0:1], s[36:37]
	s_cbranch_execz .LBB0_726
	s_waitcnt lgkmcnt(0)
	v_add_f32_e32 v66, v66, v67
	v_fma_f32 v66, v66, s6, 0.5
	v_trunc_f32_e32 v66, v66
	v_mul_f32_e32 v67, 0x2f800000, v66
	v_floor_f32_e32 v67, v67
	v_fmac_f32_e32 v66, 0xcf800000, v67
	v_cvt_u32_f32_e32 v66, v66
	v_cvt_u32_f32_e32 v67, v67
	v_lshl_add_u64 v[180:181], v[82:83], 3, s[20:21]
	v_mov_b32_e32 v182, v66
	v_mov_b32_e32 v183, v67
.LBB0_726:
	s_or_b64 exec, exec, s[0:1]
	v_add_u32_e32 v66, 0x80, v142
	s_waitcnt lgkmcnt(0)
	v_ashrrev_i32_e32 v67, 31, v66
	v_lshlrev_b64 v[68:69], 12, v[66:67]
	v_lshl_add_u64 v[68:69], s[94:95], 0, v[68:69]
	v_lshl_add_u64 v[72:73], v[140:141], 1, v[68:69]
	global_load_dwordx4 v[68:71], v[72:73], off
	v_mul_f32_e32 v62, 0xbfb8aa3b, v62
	v_mul_f32_e32 v63, 0xbfb8aa3b, v63
	v_mul_f32_e32 v64, 0xbfb8aa3b, v64
	v_mul_f32_e32 v65, 0xbfb8aa3b, v65
	v_mul_f32_e32 v54, 0xbfb8aa3b, v54
	v_mul_f32_e32 v55, 0xbfb8aa3b, v55
	v_mul_f32_e32 v56, 0xbfb8aa3b, v56
	v_mul_f32_e32 v57, 0xbfb8aa3b, v57
	v_exp_f32_e32 v62, v62
	v_exp_f32_e32 v63, v63
	v_exp_f32_e32 v64, v64
	v_exp_f32_e32 v65, v65
	v_exp_f32_e32 v54, v54
	v_exp_f32_e32 v55, v55
	v_exp_f32_e32 v56, v56
	v_exp_f32_e32 v57, v57
	v_add_f32_e32 v62, 1.0, v62
	v_add_f32_e32 v63, 1.0, v63
	v_add_f32_e32 v64, 1.0, v64
	v_add_f32_e32 v65, 1.0, v65
	v_add_f32_e32 v54, 1.0, v54
	v_add_f32_e32 v55, 1.0, v55
	v_add_f32_e32 v56, 1.0, v56
	v_add_f32_e32 v57, 1.0, v57
	v_rcp_f32_e32 v62, v62
	v_rcp_f32_e32 v63, v63
	v_rcp_f32_e32 v64, v64
	v_rcp_f32_e32 v65, v65
	v_rcp_f32_e32 v54, v54
	v_rcp_f32_e32 v55, v55
	v_rcp_f32_e32 v56, v56
	v_rcp_f32_e32 v57, v57
	s_waitcnt vmcnt(0)
	v_lshlrev_b32_e32 v74, 16, v68
	v_and_b32_e32 v68, 0xffff0000, v68
	v_lshlrev_b32_e32 v75, 16, v69
	v_and_b32_e32 v69, 0xffff0000, v69
	v_lshlrev_b32_e32 v76, 16, v70
	v_and_b32_e32 v70, 0xffff0000, v70
	v_lshlrev_b32_e32 v77, 16, v71
	v_and_b32_e32 v71, 0xffff0000, v71
	v_fmac_f32_e32 v74, v62, v58
	v_fmac_f32_e32 v68, v63, v59
	v_fmac_f32_e32 v75, v64, v60
	v_fmac_f32_e32 v69, v65, v61
	v_fmac_f32_e32 v76, v54, v50
	v_fmac_f32_e32 v70, v55, v51
	v_fmac_f32_e32 v77, v56, v52
	v_fmac_f32_e32 v71, v57, v53
	v_cvt_pk_bf16_f32 v52, v74, v68
	v_cvt_pk_bf16_f32 v53, v75, v69
	v_cvt_pk_bf16_f32 v54, v76, v70
	v_cvt_pk_bf16_f32 v55, v77, v71
	global_store_dwordx4 v[72:73], v[52:55], off
	v_and_b32_e32 v51, 0xffff0000, v52
	v_and_b32_e32 v57, 0xffff0000, v53
	v_and_b32_e32 v59, 0xffff0000, v54
	v_and_b32_e32 v61, 0xffff0000, v55
	v_lshlrev_b32_e32 v50, 16, v52
	v_lshlrev_b32_e32 v56, 16, v53
	v_lshlrev_b32_e32 v58, 16, v54
	v_lshlrev_b32_e32 v60, 16, v55
	v_mul_f32_e32 v51, v51, v51
	v_mul_f32_e32 v57, v57, v57
	v_mul_f32_e32 v59, v59, v59
	v_mul_f32_e32 v61, v61, v61
	v_fmac_f32_e32 v51, v50, v50
	v_fmac_f32_e32 v57, v56, v56
	v_fmac_f32_e32 v59, v58, v58
	v_fmac_f32_e32 v61, v60, v60
	v_add_f32_e32 v50, v51, v57
	v_add_f32_e32 v51, v59, v61
	v_add_f32_e32 v50, v50, v51
	ds_bpermute_b32 v51, v116, v50
	s_waitcnt lgkmcnt(0)
	v_add_f32_e32 v50, v50, v51
	ds_bpermute_b32 v51, v117, v50
	s_and_saveexec_b64 s[0:1], s[36:37]
	s_cbranch_execz .LBB0_728
	s_waitcnt lgkmcnt(0)
	v_add_f32_e32 v50, v50, v51
	v_fma_f32 v50, v50, s6, 0.5
	v_trunc_f32_e32 v50, v50
	v_mul_f32_e32 v51, 0x2f800000, v50
	v_floor_f32_e32 v51, v51
	v_fmac_f32_e32 v50, 0xcf800000, v51
	v_cvt_u32_f32_e32 v50, v50
	v_cvt_u32_f32_e32 v51, v51
	v_lshl_add_u64 v[184:185], v[66:67], 3, s[20:21]
	v_mov_b32_e32 v186, v50
	v_mov_b32_e32 v187, v51
.LBB0_728:
	s_or_b64 exec, exec, s[0:1]
	v_add_u32_e32 v50, 0x90, v142
	s_waitcnt lgkmcnt(0)
	v_ashrrev_i32_e32 v51, 31, v50
	v_lshlrev_b64 v[52:53], 12, v[50:51]
	v_lshl_add_u64 v[52:53], s[94:95], 0, v[52:53]
	v_lshl_add_u64 v[56:57], v[140:141], 1, v[52:53]
	global_load_dwordx4 v[52:55], v[56:57], off
	v_mul_f32_e32 v46, 0xbfb8aa3b, v46
	v_mul_f32_e32 v47, 0xbfb8aa3b, v47
	v_mul_f32_e32 v48, 0xbfb8aa3b, v48
	v_mul_f32_e32 v49, 0xbfb8aa3b, v49
	v_mul_f32_e32 v38, 0xbfb8aa3b, v38
	v_mul_f32_e32 v39, 0xbfb8aa3b, v39
	v_mul_f32_e32 v40, 0xbfb8aa3b, v40
	v_mul_f32_e32 v41, 0xbfb8aa3b, v41
	v_exp_f32_e32 v46, v46
	v_exp_f32_e32 v47, v47
	v_exp_f32_e32 v48, v48
	v_exp_f32_e32 v49, v49
	v_exp_f32_e32 v38, v38
	v_exp_f32_e32 v39, v39
	v_exp_f32_e32 v40, v40
	v_exp_f32_e32 v41, v41
	v_add_f32_e32 v46, 1.0, v46
	v_add_f32_e32 v47, 1.0, v47
	v_add_f32_e32 v48, 1.0, v48
	v_add_f32_e32 v49, 1.0, v49
	v_add_f32_e32 v38, 1.0, v38
	v_add_f32_e32 v39, 1.0, v39
	v_add_f32_e32 v40, 1.0, v40
	v_add_f32_e32 v41, 1.0, v41
	v_rcp_f32_e32 v46, v46
	v_rcp_f32_e32 v47, v47
	v_rcp_f32_e32 v48, v48
	v_rcp_f32_e32 v49, v49
	v_rcp_f32_e32 v38, v38
	v_rcp_f32_e32 v39, v39
	v_rcp_f32_e32 v40, v40
	v_rcp_f32_e32 v41, v41
	s_waitcnt vmcnt(0)
	v_lshlrev_b32_e32 v58, 16, v52
	v_and_b32_e32 v52, 0xffff0000, v52
	v_lshlrev_b32_e32 v59, 16, v53
	v_and_b32_e32 v53, 0xffff0000, v53
	v_lshlrev_b32_e32 v60, 16, v54
	v_and_b32_e32 v54, 0xffff0000, v54
	v_lshlrev_b32_e32 v61, 16, v55
	v_and_b32_e32 v55, 0xffff0000, v55
	v_fmac_f32_e32 v58, v46, v42
	v_fmac_f32_e32 v52, v47, v43
	v_fmac_f32_e32 v59, v48, v44
	v_fmac_f32_e32 v53, v49, v45
	v_fmac_f32_e32 v60, v38, v34
	v_fmac_f32_e32 v54, v39, v35
	v_fmac_f32_e32 v61, v40, v36
	v_fmac_f32_e32 v55, v41, v37
	v_cvt_pk_bf16_f32 v36, v58, v52
	v_cvt_pk_bf16_f32 v37, v59, v53
	v_cvt_pk_bf16_f32 v38, v60, v54
	v_cvt_pk_bf16_f32 v39, v61, v55
	global_store_dwordx4 v[56:57], v[36:39], off
	v_and_b32_e32 v35, 0xffff0000, v36
	v_and_b32_e32 v41, 0xffff0000, v37
	v_and_b32_e32 v43, 0xffff0000, v38
	v_and_b32_e32 v45, 0xffff0000, v39
	v_lshlrev_b32_e32 v34, 16, v36
	v_lshlrev_b32_e32 v40, 16, v37
	v_lshlrev_b32_e32 v42, 16, v38
	v_lshlrev_b32_e32 v44, 16, v39
	v_mul_f32_e32 v35, v35, v35
	v_mul_f32_e32 v41, v41, v41
	v_mul_f32_e32 v43, v43, v43
	v_mul_f32_e32 v45, v45, v45
	v_fmac_f32_e32 v35, v34, v34
	v_fmac_f32_e32 v41, v40, v40
	v_fmac_f32_e32 v43, v42, v42
	v_fmac_f32_e32 v45, v44, v44
	v_add_f32_e32 v34, v35, v41
	v_add_f32_e32 v35, v43, v45
	v_add_f32_e32 v34, v34, v35
	ds_bpermute_b32 v35, v116, v34
	s_waitcnt lgkmcnt(0)
	v_add_f32_e32 v34, v34, v35
	ds_bpermute_b32 v35, v117, v34
	s_and_saveexec_b64 s[0:1], s[36:37]
	s_cbranch_execz .LBB0_730
	s_waitcnt lgkmcnt(0)
	v_add_f32_e32 v34, v34, v35
	v_fma_f32 v34, v34, s6, 0.5
	v_trunc_f32_e32 v34, v34
	v_mul_f32_e32 v35, 0x2f800000, v34
	v_floor_f32_e32 v35, v35
	v_fmac_f32_e32 v34, 0xcf800000, v35
	v_cvt_u32_f32_e32 v34, v34
	v_cvt_u32_f32_e32 v35, v35
	v_lshl_add_u64 v[188:189], v[50:51], 3, s[20:21]
	v_mov_b32_e32 v190, v34
	v_mov_b32_e32 v191, v35
.LBB0_730:
	s_or_b64 exec, exec, s[0:1]
	v_add_u32_e32 v34, 0xa0, v142
	s_waitcnt lgkmcnt(0)
	v_ashrrev_i32_e32 v35, 31, v34
	v_lshlrev_b64 v[36:37], 12, v[34:35]
	v_lshl_add_u64 v[36:37], s[94:95], 0, v[36:37]
	v_lshl_add_u64 v[40:41], v[140:141], 1, v[36:37]
	global_load_dwordx4 v[36:39], v[40:41], off
	v_mul_f32_e32 v30, 0xbfb8aa3b, v30
	v_mul_f32_e32 v31, 0xbfb8aa3b, v31
	v_mul_f32_e32 v32, 0xbfb8aa3b, v32
	v_mul_f32_e32 v33, 0xbfb8aa3b, v33
	v_mul_f32_e32 v22, 0xbfb8aa3b, v22
	v_mul_f32_e32 v23, 0xbfb8aa3b, v23
	v_mul_f32_e32 v24, 0xbfb8aa3b, v24
	v_mul_f32_e32 v25, 0xbfb8aa3b, v25
	v_exp_f32_e32 v30, v30
	v_exp_f32_e32 v31, v31
	v_exp_f32_e32 v32, v32
	v_exp_f32_e32 v33, v33
	v_exp_f32_e32 v22, v22
	v_exp_f32_e32 v23, v23
	v_exp_f32_e32 v24, v24
	v_exp_f32_e32 v25, v25
	v_add_f32_e32 v30, 1.0, v30
	v_add_f32_e32 v31, 1.0, v31
	v_add_f32_e32 v32, 1.0, v32
	v_add_f32_e32 v33, 1.0, v33
	v_add_f32_e32 v22, 1.0, v22
	v_add_f32_e32 v23, 1.0, v23
	v_add_f32_e32 v24, 1.0, v24
	v_add_f32_e32 v25, 1.0, v25
	v_rcp_f32_e32 v30, v30
	v_rcp_f32_e32 v31, v31
	v_rcp_f32_e32 v32, v32
	v_rcp_f32_e32 v33, v33
	v_rcp_f32_e32 v22, v22
	v_rcp_f32_e32 v23, v23
	v_rcp_f32_e32 v24, v24
	v_rcp_f32_e32 v25, v25
	s_waitcnt vmcnt(0)
	v_lshlrev_b32_e32 v42, 16, v36
	v_and_b32_e32 v36, 0xffff0000, v36
	v_lshlrev_b32_e32 v43, 16, v37
	v_and_b32_e32 v37, 0xffff0000, v37
	v_lshlrev_b32_e32 v44, 16, v38
	v_and_b32_e32 v38, 0xffff0000, v38
	v_lshlrev_b32_e32 v45, 16, v39
	v_and_b32_e32 v39, 0xffff0000, v39
	v_fmac_f32_e32 v42, v30, v26
	v_fmac_f32_e32 v36, v31, v27
	v_fmac_f32_e32 v43, v32, v28
	v_fmac_f32_e32 v37, v33, v29
	v_fmac_f32_e32 v44, v22, v18
	v_fmac_f32_e32 v38, v23, v19
	v_fmac_f32_e32 v45, v24, v20
	v_fmac_f32_e32 v39, v25, v21
	v_cvt_pk_bf16_f32 v20, v42, v36
	v_cvt_pk_bf16_f32 v21, v43, v37
	v_cvt_pk_bf16_f32 v22, v44, v38
	v_cvt_pk_bf16_f32 v23, v45, v39
	global_store_dwordx4 v[40:41], v[20:23], off
	v_and_b32_e32 v19, 0xffff0000, v20
	v_and_b32_e32 v25, 0xffff0000, v21
	v_and_b32_e32 v27, 0xffff0000, v22
	v_and_b32_e32 v29, 0xffff0000, v23
	v_lshlrev_b32_e32 v18, 16, v20
	v_lshlrev_b32_e32 v24, 16, v21
	v_lshlrev_b32_e32 v26, 16, v22
	v_lshlrev_b32_e32 v28, 16, v23
	v_mul_f32_e32 v19, v19, v19
	v_mul_f32_e32 v25, v25, v25
	v_mul_f32_e32 v27, v27, v27
	v_mul_f32_e32 v29, v29, v29
	v_fmac_f32_e32 v19, v18, v18
	v_fmac_f32_e32 v25, v24, v24
	v_fmac_f32_e32 v27, v26, v26
	v_fmac_f32_e32 v29, v28, v28
	v_add_f32_e32 v18, v19, v25
	v_add_f32_e32 v19, v27, v29
	v_add_f32_e32 v18, v18, v19
	ds_bpermute_b32 v19, v116, v18
	s_waitcnt lgkmcnt(0)
	v_add_f32_e32 v18, v18, v19
	ds_bpermute_b32 v19, v117, v18
	s_and_saveexec_b64 s[0:1], s[36:37]
	s_cbranch_execz .LBB0_732
	s_waitcnt lgkmcnt(0)
	v_add_f32_e32 v18, v18, v19
	v_fma_f32 v18, v18, s6, 0.5
	v_trunc_f32_e32 v18, v18
	v_mul_f32_e32 v19, 0x2f800000, v18
	v_floor_f32_e32 v19, v19
	v_fmac_f32_e32 v18, 0xcf800000, v19
	v_cvt_u32_f32_e32 v18, v18
	v_cvt_u32_f32_e32 v19, v19
	v_lshl_add_u64 v[192:193], v[34:35], 3, s[20:21]
	v_mov_b32_e32 v194, v18
	v_mov_b32_e32 v195, v19

.LBB0_734:
	s_or_b64 exec, exec, s[0:1]
	s_and_saveexec_b64 s[0:1], s[36:37]
	global_atomic_add_x2 v[168:169], v[170:171], off
	global_atomic_add_x2 v[172:173], v[174:175], off
	global_atomic_add_x2 v[176:177], v[178:179], off
	global_atomic_add_x2 v[180:181], v[182:183], off
	global_atomic_add_x2 v[184:185], v[186:187], off
	global_atomic_add_x2 v[188:189], v[190:191], off
	global_atomic_add_x2 v[192:193], v[194:195], off
	s_or_b64 exec, exec, s[0:1]
	s_and_b64 vcc, exec, s[40:41]
	s_mov_b64 s[0:1], -1
	s_cbranch_vccnz .LBB0_711
	s_andn2_b64 vcc, exec, s[12:13]
	s_cbranch_vccnz .LBB0_710
	s_barrier
	s_branch .LBB0_710

.LBB0_1610:
	v_lshl_add_u32 v142, s12, 8, v1
	v_ashrrev_i32_e32 v143, 31, v142
	v_lshl_or_b32 v140, s0, 8, v145
	v_lshlrev_b64 v[148:149], 12, v[142:143]
	v_ashrrev_i32_e32 v141, 31, v140
	v_lshl_add_u64 v[148:149], s[94:95], 0, v[148:149]
	v_lshl_add_u64 v[152:153], v[140:141], 1, v[148:149]
	global_load_dwordx4 v[148:151], v[152:153], off
	s_waitcnt vmcnt(0)
	v_lshlrev_b32_e32 v147, 16, v148
	v_and_b32_e32 v148, 0xffff0000, v148
	v_lshlrev_b32_e32 v156, 16, v151
	v_and_b32_e32 v151, 0xffff0000, v151
	v_lshlrev_b32_e32 v154, 16, v149
	v_and_b32_e32 v149, 0xffff0000, v149
	v_lshlrev_b32_e32 v155, 16, v150
	v_and_b32_e32 v150, 0xffff0000, v150
	v_add_f32_e32 v126, v126, v147
	v_add_f32_e32 v127, v127, v148
	v_add_f32_e32 v148, v125, v151
	v_add_f32_e32 v128, v128, v154
	v_add_f32_e32 v129, v129, v149
	v_add_f32_e32 v122, v122, v155
	v_add_f32_e32 v123, v123, v150
	v_add_f32_e32 v147, v124, v156
	v_cvt_pk_bf16_f32 v124, v126, v127
	v_cvt_pk_bf16_f32 v125, v128, v129
	v_cvt_pk_bf16_f32 v126, v122, v123
	v_cvt_pk_bf16_f32 v127, v147, v148
	global_load_dwordx4 v[148:151], v[152:153], off offset:256
	v_lshlrev_b32_e32 v128, 16, v124
	global_store_dwordx4 v[152:153], v[124:127], off
	v_lshlrev_b32_e32 v129, 16, v125
	v_lshlrev_b32_e32 v147, 16, v126
	v_and_b32_e32 v124, 0xffff0000, v124
	v_and_b32_e32 v125, 0xffff0000, v125
	v_and_b32_e32 v126, 0xffff0000, v126
	v_lshlrev_b32_e32 v154, 16, v127
	v_and_b32_e32 v127, 0xffff0000, v127
	v_mul_f32_e32 v124, v124, v124
	v_mul_f32_e32 v125, v125, v125
	v_mul_f32_e32 v126, v126, v126
	v_mul_f32_e32 v127, v127, v127
	v_fmac_f32_e32 v124, v128, v128
	v_fmac_f32_e32 v125, v129, v129
	v_fmac_f32_e32 v126, v147, v147
	v_fmac_f32_e32 v127, v154, v154
	v_add_f32_e32 v124, v124, v125
	v_add_f32_e32 v125, v126, v127
	v_add_f32_e32 v124, v124, v125
	v_and_b32_e32 v123, 64, v212
	v_xor_b32_e32 v122, 16, v212
	v_add_u32_e32 v123, 64, v123
	v_cmp_lt_i32_e32 vcc, v122, v123
	s_waitcnt vmcnt(1)
	v_lshlrev_b32_e32 v125, 16, v148
	v_and_b32_e32 v126, 0xffff0000, v148
	v_lshlrev_b32_e32 v127, 16, v149
	v_and_b32_e32 v128, 0xffff0000, v149
	v_and_b32_e32 v147, 0xffff0000, v150
	v_and_b32_e32 v149, 0xffff0000, v151
	v_lshlrev_b32_e32 v129, 16, v150
	v_lshlrev_b32_e32 v148, 16, v151
	v_add_f32_e32 v118, v118, v125
	v_add_f32_e32 v119, v119, v126
	v_add_f32_e32 v120, v120, v127
	v_add_f32_e32 v121, v121, v128
	v_add_f32_e32 v115, v115, v147
	v_add_f32_e32 v117, v117, v149
	v_add_f32_e32 v114, v114, v129
	v_add_f32_e32 v116, v116, v148
	v_cvt_pk_bf16_f32 v118, v118, v119
	v_cvt_pk_bf16_f32 v119, v120, v121
	v_cvt_pk_bf16_f32 v120, v114, v115
	v_cvt_pk_bf16_f32 v121, v116, v117
	v_cndmask_b32_e32 v122, v212, v122, vcc
	v_and_b32_e32 v115, 0xffff0000, v118
	v_and_b32_e32 v117, 0xffff0000, v119
	v_and_b32_e32 v126, 0xffff0000, v120
	v_and_b32_e32 v128, 0xffff0000, v121
	v_lshlrev_b32_e32 v114, 16, v118
	v_lshlrev_b32_e32 v116, 16, v119
	v_lshlrev_b32_e32 v125, 16, v120
	v_lshlrev_b32_e32 v127, 16, v121
	v_mul_f32_e32 v115, v115, v115
	v_mul_f32_e32 v117, v117, v117
	v_mul_f32_e32 v126, v126, v126
	v_mul_f32_e32 v128, v128, v128
	v_fmac_f32_e32 v115, v114, v114
	v_fmac_f32_e32 v117, v116, v116
	v_fmac_f32_e32 v126, v125, v125
	v_fmac_f32_e32 v128, v127, v127
	v_add_f32_e32 v114, v115, v117
	v_add_f32_e32 v115, v126, v128
	v_add_f32_e32 v114, v114, v115
	v_lshlrev_b32_e32 v122, 2, v122
	v_add_f32_e32 v114, v124, v114
	ds_bpermute_b32 v115, v122, v114
	v_xor_b32_e32 v116, 32, v212
	v_cmp_lt_i32_e32 vcc, v116, v123
	global_store_dwordx4 v[152:153], v[118:121], off offset:256
	s_waitcnt lgkmcnt(0)
	v_add_f32_e32 v114, v114, v115
	v_cndmask_b32_e32 v116, v212, v116, vcc
	v_lshlrev_b32_e32 v116, 2, v116
	ds_bpermute_b32 v115, v116, v114
	s_and_saveexec_b64 s[0:1], s[36:37]
	s_cbranch_execz .LBB0_1612
	s_waitcnt lgkmcnt(0)
	v_add_f32_e32 v114, v114, v115
	v_fma_f32 v114, v114, s6, 0.5
	v_trunc_f32_e32 v114, v114
	v_mul_f32_e32 v115, 0x2f800000, v114
	v_floor_f32_e32 v115, v115
	v_fmac_f32_e32 v114, 0xcf800000, v115
	v_cvt_u32_f32_e32 v114, v114
	v_cvt_u32_f32_e32 v115, v115
	v_lshl_add_u64 v[168:169], v[142:143], 3, s[40:41]
	v_mov_b32_e32 v170, v114
	v_mov_b32_e32 v171, v115
.LBB0_1612:
	s_or_b64 exec, exec, s[0:1]
	v_or_b32_e32 v114, 16, v142
	s_waitcnt lgkmcnt(0)
	v_ashrrev_i32_e32 v115, 31, v114
	v_lshlrev_b64 v[118:119], 12, v[114:115]
	v_lshl_add_u64 v[118:119], s[94:95], 0, v[118:119]
	v_lshl_add_u64 v[124:125], v[140:141], 1, v[118:119]
	global_load_dwordx4 v[118:121], v[124:125], off
	s_waitcnt vmcnt(0)
	v_lshlrev_b32_e32 v117, 16, v118
	v_and_b32_e32 v118, 0xffff0000, v118
	v_lshlrev_b32_e32 v123, 16, v119
	v_and_b32_e32 v119, 0xffff0000, v119
	v_lshlrev_b32_e32 v127, 16, v121
	v_and_b32_e32 v121, 0xffff0000, v121
	v_lshlrev_b32_e32 v126, 16, v120
	v_and_b32_e32 v120, 0xffff0000, v120
	v_add_f32_e32 v110, v110, v117
	v_add_f32_e32 v111, v111, v118
	v_add_f32_e32 v112, v112, v123
	v_add_f32_e32 v113, v113, v119
	v_add_f32_e32 v109, v109, v121
	v_add_f32_e32 v117, v106, v126
	v_add_f32_e32 v118, v107, v120
	v_add_f32_e32 v119, v108, v127
	v_cvt_pk_bf16_f32 v106, v110, v111
	v_cvt_pk_bf16_f32 v107, v112, v113
	v_cvt_pk_bf16_f32 v108, v117, v118
	v_cvt_pk_bf16_f32 v109, v119, v109
	global_load_dwordx4 v[110:113], v[124:125], off offset:256
	v_lshlrev_b32_e32 v117, 16, v106
	global_store_dwordx4 v[124:125], v[106:109], off
	v_lshlrev_b32_e32 v118, 16, v107
	v_lshlrev_b32_e32 v119, 16, v108
	v_and_b32_e32 v106, 0xffff0000, v106
	v_and_b32_e32 v107, 0xffff0000, v107
	v_and_b32_e32 v108, 0xffff0000, v108
	v_lshlrev_b32_e32 v120, 16, v109
	v_and_b32_e32 v109, 0xffff0000, v109
	v_mul_f32_e32 v106, v106, v106
	v_mul_f32_e32 v107, v107, v107
	v_mul_f32_e32 v108, v108, v108
	v_mul_f32_e32 v109, v109, v109
	v_fmac_f32_e32 v106, v117, v117
	v_fmac_f32_e32 v107, v118, v118
	v_fmac_f32_e32 v108, v119, v119
	v_fmac_f32_e32 v109, v120, v120
	v_add_f32_e32 v106, v106, v107
	v_add_f32_e32 v107, v108, v109
	v_add_f32_e32 v106, v106, v107
	s_waitcnt vmcnt(1)
	v_lshlrev_b32_e32 v107, 16, v110
	v_and_b32_e32 v108, 0xffff0000, v110
	v_lshlrev_b32_e32 v109, 16, v111
	v_and_b32_e32 v110, 0xffff0000, v111
	v_lshlrev_b32_e32 v111, 16, v112
	v_and_b32_e32 v112, 0xffff0000, v112
	v_lshlrev_b32_e32 v117, 16, v113
	v_and_b32_e32 v113, 0xffff0000, v113
	v_add_f32_e32 v102, v102, v107
	v_add_f32_e32 v103, v103, v108
	v_add_f32_e32 v105, v105, v110
	v_add_f32_e32 v99, v99, v112
	v_add_f32_e32 v108, v101, v113
	v_add_f32_e32 v104, v104, v109
	v_add_f32_e32 v98, v98, v111
	v_add_f32_e32 v107, v100, v117
	v_cvt_pk_bf16_f32 v100, v102, v103
	v_cvt_pk_bf16_f32 v101, v104, v105
	v_cvt_pk_bf16_f32 v102, v98, v99
	v_cvt_pk_bf16_f32 v103, v107, v108
	global_store_dwordx4 v[124:125], v[100:103], off offset:256
	v_and_b32_e32 v99, 0xffff0000, v100
	v_and_b32_e32 v105, 0xffff0000, v101
	v_and_b32_e32 v108, 0xffff0000, v102
	v_and_b32_e32 v110, 0xffff0000, v103
	v_lshlrev_b32_e32 v98, 16, v100
	v_lshlrev_b32_e32 v104, 16, v101
	v_lshlrev_b32_e32 v107, 16, v102
	v_lshlrev_b32_e32 v109, 16, v103
	v_mul_f32_e32 v99, v99, v99
	v_mul_f32_e32 v105, v105, v105
	v_mul_f32_e32 v108, v108, v108
	v_mul_f32_e32 v110, v110, v110
	v_fmac_f32_e32 v99, v98, v98
	v_fmac_f32_e32 v105, v104, v104
	v_fmac_f32_e32 v108, v107, v107
	v_fmac_f32_e32 v110, v109, v109
	v_add_f32_e32 v98, v99, v105
	v_add_f32_e32 v99, v108, v110
	v_add_f32_e32 v98, v98, v99
	v_add_f32_e32 v98, v106, v98
	ds_bpermute_b32 v99, v122, v98
	s_waitcnt lgkmcnt(0)
	v_add_f32_e32 v98, v98, v99
	ds_bpermute_b32 v99, v116, v98
	s_and_saveexec_b64 s[0:1], s[36:37]
	s_cbranch_execz .LBB0_1614
	s_waitcnt lgkmcnt(0)
	v_add_f32_e32 v98, v98, v99
	v_fma_f32 v98, v98, s6, 0.5
	v_trunc_f32_e32 v98, v98
	v_mul_f32_e32 v99, 0x2f800000, v98
	v_floor_f32_e32 v99, v99
	v_fmac_f32_e32 v98, 0xcf800000, v99
	v_cvt_u32_f32_e32 v98, v98
	v_cvt_u32_f32_e32 v99, v99
	v_lshl_add_u64 v[172:173], v[114:115], 3, s[40:41]
	v_mov_b32_e32 v174, v98
	v_mov_b32_e32 v175, v99
.LBB0_1614:
	s_or_b64 exec, exec, s[0:1]
	v_or_b32_e32 v98, 32, v142
	s_waitcnt lgkmcnt(0)
	v_ashrrev_i32_e32 v99, 31, v98
	v_lshlrev_b64 v[100:101], 12, v[98:99]
	v_lshl_add_u64 v[100:101], s[94:95], 0, v[100:101]
	v_lshl_add_u64 v[104:105], v[140:141], 1, v[100:101]
	global_load_dwordx4 v[100:103], v[104:105], off
	s_waitcnt vmcnt(0)
	v_lshlrev_b32_e32 v106, 16, v100
	v_and_b32_e32 v100, 0xffff0000, v100
	v_lshlrev_b32_e32 v107, 16, v101
	v_and_b32_e32 v101, 0xffff0000, v101
	v_lshlrev_b32_e32 v109, 16, v103
	v_and_b32_e32 v103, 0xffff0000, v103
	v_lshlrev_b32_e32 v108, 16, v102
	v_and_b32_e32 v102, 0xffff0000, v102
	v_add_f32_e32 v94, v94, v106
	v_add_f32_e32 v95, v95, v100
	v_add_f32_e32 v96, v96, v107
	v_add_f32_e32 v97, v97, v101
	v_add_f32_e32 v93, v93, v103
	v_add_f32_e32 v100, v90, v108
	v_add_f32_e32 v101, v91, v102
	v_add_f32_e32 v102, v92, v109
	v_cvt_pk_bf16_f32 v90, v94, v95
	v_cvt_pk_bf16_f32 v91, v96, v97
	v_cvt_pk_bf16_f32 v92, v100, v101
	v_cvt_pk_bf16_f32 v93, v102, v93
	global_load_dwordx4 v[94:97], v[104:105], off offset:256
	v_lshlrev_b32_e32 v100, 16, v90
	global_store_dwordx4 v[104:105], v[90:93], off
	v_lshlrev_b32_e32 v101, 16, v91
	v_lshlrev_b32_e32 v102, 16, v92
	v_and_b32_e32 v90, 0xffff0000, v90
	v_and_b32_e32 v91, 0xffff0000, v91
	v_and_b32_e32 v92, 0xffff0000, v92
	v_lshlrev_b32_e32 v103, 16, v93
	v_and_b32_e32 v93, 0xffff0000, v93
	v_mul_f32_e32 v90, v90, v90
	v_mul_f32_e32 v91, v91, v91
	v_mul_f32_e32 v92, v92, v92
	v_mul_f32_e32 v93, v93, v93
	v_fmac_f32_e32 v90, v100, v100
	v_fmac_f32_e32 v91, v101, v101
	v_fmac_f32_e32 v92, v102, v102
	v_fmac_f32_e32 v93, v103, v103
	v_add_f32_e32 v90, v90, v91
	v_add_f32_e32 v91, v92, v93
	v_add_f32_e32 v90, v90, v91
	s_waitcnt vmcnt(1)
	v_lshlrev_b32_e32 v91, 16, v94
	v_and_b32_e32 v92, 0xffff0000, v94
	v_lshlrev_b32_e32 v93, 16, v95
	v_and_b32_e32 v94, 0xffff0000, v95
	v_lshlrev_b32_e32 v95, 16, v96
	v_and_b32_e32 v96, 0xffff0000, v96
	v_lshlrev_b32_e32 v100, 16, v97
	v_and_b32_e32 v97, 0xffff0000, v97
	v_add_f32_e32 v86, v86, v91
	v_add_f32_e32 v87, v87, v92
	v_add_f32_e32 v89, v89, v94
	v_add_f32_e32 v83, v83, v96
	v_add_f32_e32 v92, v85, v97
	v_add_f32_e32 v88, v88, v93
	v_add_f32_e32 v82, v82, v95
	v_add_f32_e32 v91, v84, v100
	v_cvt_pk_bf16_f32 v84, v86, v87
	v_cvt_pk_bf16_f32 v85, v88, v89
	v_cvt_pk_bf16_f32 v86, v82, v83
	v_cvt_pk_bf16_f32 v87, v91, v92
	global_store_dwordx4 v[104:105], v[84:87], off offset:256
	v_and_b32_e32 v83, 0xffff0000, v84
	v_and_b32_e32 v89, 0xffff0000, v85
	v_and_b32_e32 v92, 0xffff0000, v86
	v_and_b32_e32 v94, 0xffff0000, v87
	v_lshlrev_b32_e32 v82, 16, v84
	v_lshlrev_b32_e32 v88, 16, v85
	v_lshlrev_b32_e32 v91, 16, v86
	v_lshlrev_b32_e32 v93, 16, v87
	v_mul_f32_e32 v83, v83, v83
	v_mul_f32_e32 v89, v89, v89
	v_mul_f32_e32 v92, v92, v92
	v_mul_f32_e32 v94, v94, v94
	v_fmac_f32_e32 v83, v82, v82
	v_fmac_f32_e32 v89, v88, v88
	v_fmac_f32_e32 v92, v91, v91
	v_fmac_f32_e32 v94, v93, v93
	v_add_f32_e32 v82, v83, v89
	v_add_f32_e32 v83, v92, v94
	v_add_f32_e32 v82, v82, v83
	v_add_f32_e32 v82, v90, v82
	ds_bpermute_b32 v83, v122, v82
	s_waitcnt lgkmcnt(0)
	v_add_f32_e32 v82, v82, v83
	ds_bpermute_b32 v83, v116, v82
	s_and_saveexec_b64 s[0:1], s[36:37]
	s_cbranch_execz .LBB0_1616
	s_waitcnt lgkmcnt(0)
	v_add_f32_e32 v82, v82, v83
	v_fma_f32 v82, v82, s6, 0.5
	v_trunc_f32_e32 v82, v82
	v_mul_f32_e32 v83, 0x2f800000, v82
	v_floor_f32_e32 v83, v83
	v_fmac_f32_e32 v82, 0xcf800000, v83
	v_cvt_u32_f32_e32 v82, v82
	v_cvt_u32_f32_e32 v83, v83
	v_lshl_add_u64 v[176:177], v[98:99], 3, s[40:41]
	v_mov_b32_e32 v178, v82
	v_mov_b32_e32 v179, v83
.LBB0_1616:
	s_or_b64 exec, exec, s[0:1]
	v_or_b32_e32 v82, 48, v142
	s_waitcnt lgkmcnt(0)
	v_ashrrev_i32_e32 v83, 31, v82
	v_lshlrev_b64 v[84:85], 12, v[82:83]
	v_lshl_add_u64 v[84:85], s[94:95], 0, v[84:85]
	v_lshl_add_u64 v[84:85], v[140:141], 1, v[84:85]
	global_load_dwordx4 v[86:89], v[84:85], off
	s_waitcnt vmcnt(0)
	v_lshlrev_b32_e32 v90, 16, v86
	v_and_b32_e32 v86, 0xffff0000, v86
	v_add_f32_e32 v78, v78, v90
	v_add_f32_e32 v79, v79, v86
	v_cvt_pk_bf16_f32 v78, v78, v79
	v_lshlrev_b32_e32 v79, 16, v87
	v_add_f32_e32 v79, v80, v79
	v_and_b32_e32 v80, 0xffff0000, v87
	v_add_f32_e32 v80, v81, v80
	v_cvt_pk_bf16_f32 v79, v79, v80
	v_lshlrev_b32_e32 v80, 16, v88
	v_add_f32_e32 v74, v74, v80
	v_and_b32_e32 v80, 0xffff0000, v88
	v_add_f32_e32 v75, v75, v80
	v_cvt_pk_bf16_f32 v80, v74, v75
	v_and_b32_e32 v75, 0xffff0000, v89
	v_lshlrev_b32_e32 v74, 16, v89
	v_add_f32_e32 v75, v77, v75
	v_add_f32_e32 v74, v76, v74
	v_cvt_pk_bf16_f32 v81, v74, v75
	v_and_b32_e32 v75, 0xffff0000, v78
	v_lshlrev_b32_e32 v74, 16, v78
	v_and_b32_e32 v77, 0xffff0000, v79
	v_mul_f32_e32 v75, v75, v75
	v_lshlrev_b32_e32 v76, 16, v79
	v_fmac_f32_e32 v75, v74, v74
	v_mul_f32_e32 v74, v77, v77
	global_store_dwordx4 v[84:85], v[78:81], off
	v_fmac_f32_e32 v74, v76, v76
	v_add_f32_e32 v74, v75, v74
	v_lshlrev_b32_e32 v78, 16, v80
	v_and_b32_e32 v79, 0xffff0000, v80
	v_lshlrev_b32_e32 v80, 16, v81
	v_and_b32_e32 v81, 0xffff0000, v81
	v_mul_f32_e32 v75, v79, v79
	v_mul_f32_e32 v76, v81, v81
	v_fmac_f32_e32 v75, v78, v78
	v_fmac_f32_e32 v76, v80, v80
	v_add_f32_e32 v75, v75, v76
	v_add_f32_e32 v78, v74, v75
	global_load_dwordx4 v[74:77], v[84:85], off offset:256
	s_waitcnt vmcnt(0)
	v_lshlrev_b32_e32 v79, 16, v74
	v_and_b32_e32 v74, 0xffff0000, v74
	v_add_f32_e32 v70, v70, v79
	v_add_f32_e32 v71, v71, v74
	v_cvt_pk_bf16_f32 v70, v70, v71
	v_lshlrev_b32_e32 v71, 16, v75
	v_add_f32_e32 v71, v72, v71
	v_and_b32_e32 v72, 0xffff0000, v75
	v_add_f32_e32 v72, v73, v72
	v_cvt_pk_bf16_f32 v71, v71, v72
	v_lshlrev_b32_e32 v72, 16, v76
	v_add_f32_e32 v66, v66, v72
	v_and_b32_e32 v72, 0xffff0000, v76
	v_add_f32_e32 v67, v67, v72
	v_cvt_pk_bf16_f32 v72, v66, v67
	v_and_b32_e32 v67, 0xffff0000, v77
	v_lshlrev_b32_e32 v66, 16, v77
	v_add_f32_e32 v67, v69, v67
	v_add_f32_e32 v66, v68, v66
	v_cvt_pk_bf16_f32 v73, v66, v67
	v_and_b32_e32 v67, 0xffff0000, v70
	v_lshlrev_b32_e32 v66, 16, v70
	v_and_b32_e32 v69, 0xffff0000, v71
	v_mul_f32_e32 v67, v67, v67
	v_lshlrev_b32_e32 v68, 16, v71
	v_fmac_f32_e32 v67, v66, v66
	v_mul_f32_e32 v66, v69, v69
	global_store_dwordx4 v[84:85], v[70:73], off offset:256
	v_fmac_f32_e32 v66, v68, v68
	v_add_f32_e32 v66, v67, v66
	v_lshlrev_b32_e32 v70, 16, v72
	v_and_b32_e32 v71, 0xffff0000, v72
	v_lshlrev_b32_e32 v72, 16, v73
	v_and_b32_e32 v73, 0xffff0000, v73
	v_mul_f32_e32 v67, v71, v71
	v_mul_f32_e32 v68, v73, v73
	v_fmac_f32_e32 v67, v70, v70
	v_fmac_f32_e32 v68, v72, v72
	v_add_f32_e32 v67, v67, v68
	v_add_f32_e32 v66, v66, v67
	v_add_f32_e32 v66, v78, v66
	ds_bpermute_b32 v67, v122, v66
	s_waitcnt lgkmcnt(0)
	v_add_f32_e32 v66, v66, v67
	ds_bpermute_b32 v67, v116, v66
	s_and_saveexec_b64 s[0:1], s[36:37]
	s_cbranch_execz .LBB0_1618
	s_waitcnt lgkmcnt(0)
	v_add_f32_e32 v66, v66, v67
	v_fma_f32 v66, v66, s6, 0.5
	v_trunc_f32_e32 v66, v66
	v_mul_f32_e32 v67, 0x2f800000, v66
	v_floor_f32_e32 v67, v67
	v_fmac_f32_e32 v66, 0xcf800000, v67
	v_cvt_u32_f32_e32 v66, v66
	v_cvt_u32_f32_e32 v67, v67
	v_lshl_add_u64 v[180:181], v[82:83], 3, s[40:41]
	v_mov_b32_e32 v182, v66
	v_mov_b32_e32 v183, v67
.LBB0_1618:
	s_or_b64 exec, exec, s[0:1]
	v_add_u32_e32 v66, 0x80, v142
	s_waitcnt lgkmcnt(0)
	v_ashrrev_i32_e32 v67, 31, v66
	v_lshlrev_b64 v[68:69], 12, v[66:67]
	v_lshl_add_u64 v[68:69], s[94:95], 0, v[68:69]
	v_lshl_add_u64 v[72:73], v[140:141], 1, v[68:69]
	global_load_dwordx4 v[68:71], v[72:73], off
	s_waitcnt vmcnt(0)
	v_lshlrev_b32_e32 v74, 16, v68
	v_and_b32_e32 v68, 0xffff0000, v68
	v_lshlrev_b32_e32 v75, 16, v69
	v_and_b32_e32 v69, 0xffff0000, v69
	v_lshlrev_b32_e32 v77, 16, v71
	v_and_b32_e32 v71, 0xffff0000, v71
	v_lshlrev_b32_e32 v76, 16, v70
	v_and_b32_e32 v70, 0xffff0000, v70
	v_add_f32_e32 v62, v62, v74
	v_add_f32_e32 v63, v63, v68
	v_add_f32_e32 v64, v64, v75
	v_add_f32_e32 v65, v65, v69
	v_add_f32_e32 v61, v61, v71
	v_add_f32_e32 v68, v58, v76
	v_add_f32_e32 v69, v59, v70
	v_add_f32_e32 v70, v60, v77
	v_cvt_pk_bf16_f32 v58, v62, v63
	v_cvt_pk_bf16_f32 v59, v64, v65
	v_cvt_pk_bf16_f32 v60, v68, v69
	v_cvt_pk_bf16_f32 v61, v70, v61
	global_load_dwordx4 v[62:65], v[72:73], off offset:256
	v_lshlrev_b32_e32 v68, 16, v58
	global_store_dwordx4 v[72:73], v[58:61], off
	v_lshlrev_b32_e32 v69, 16, v59
	v_lshlrev_b32_e32 v70, 16, v60
	v_and_b32_e32 v58, 0xffff0000, v58
	v_and_b32_e32 v59, 0xffff0000, v59
	v_and_b32_e32 v60, 0xffff0000, v60
	v_lshlrev_b32_e32 v71, 16, v61
	v_and_b32_e32 v61, 0xffff0000, v61
	v_mul_f32_e32 v58, v58, v58
	v_mul_f32_e32 v59, v59, v59
	v_mul_f32_e32 v60, v60, v60
	v_mul_f32_e32 v61, v61, v61
	v_fmac_f32_e32 v58, v68, v68
	v_fmac_f32_e32 v59, v69, v69
	v_fmac_f32_e32 v60, v70, v70
	v_fmac_f32_e32 v61, v71, v71
	v_add_f32_e32 v58, v58, v59
	v_add_f32_e32 v59, v60, v61
	v_add_f32_e32 v58, v58, v59
	s_waitcnt vmcnt(1)
	v_lshlrev_b32_e32 v59, 16, v62
	v_and_b32_e32 v60, 0xffff0000, v62
	v_lshlrev_b32_e32 v61, 16, v63
	v_and_b32_e32 v62, 0xffff0000, v63
	v_lshlrev_b32_e32 v63, 16, v64
	v_and_b32_e32 v64, 0xffff0000, v64
	v_lshlrev_b32_e32 v68, 16, v65
	v_and_b32_e32 v65, 0xffff0000, v65
	v_add_f32_e32 v54, v54, v59
	v_add_f32_e32 v55, v55, v60
	v_add_f32_e32 v57, v57, v62
	v_add_f32_e32 v51, v51, v64
	v_add_f32_e32 v60, v53, v65
	v_add_f32_e32 v56, v56, v61
	v_add_f32_e32 v50, v50, v63
	v_add_f32_e32 v59, v52, v68
	v_cvt_pk_bf16_f32 v52, v54, v55
	v_cvt_pk_bf16_f32 v53, v56, v57
	v_cvt_pk_bf16_f32 v54, v50, v51
	v_cvt_pk_bf16_f32 v55, v59, v60
	global_store_dwordx4 v[72:73], v[52:55], off offset:256
	v_and_b32_e32 v51, 0xffff0000, v52
	v_and_b32_e32 v57, 0xffff0000, v53
	v_and_b32_e32 v60, 0xffff0000, v54
	v_and_b32_e32 v62, 0xffff0000, v55
	v_lshlrev_b32_e32 v50, 16, v52
	v_lshlrev_b32_e32 v56, 16, v53
	v_lshlrev_b32_e32 v59, 16, v54
	v_lshlrev_b32_e32 v61, 16, v55
	v_mul_f32_e32 v51, v51, v51
	v_mul_f32_e32 v57, v57, v57
	v_mul_f32_e32 v60, v60, v60
	v_mul_f32_e32 v62, v62, v62
	v_fmac_f32_e32 v51, v50, v50
	v_fmac_f32_e32 v57, v56, v56
	v_fmac_f32_e32 v60, v59, v59
	v_fmac_f32_e32 v62, v61, v61
	v_add_f32_e32 v50, v51, v57
	v_add_f32_e32 v51, v60, v62
	v_add_f32_e32 v50, v50, v51
	v_add_f32_e32 v50, v58, v50
	ds_bpermute_b32 v51, v122, v50
	s_waitcnt lgkmcnt(0)
	v_add_f32_e32 v50, v50, v51
	ds_bpermute_b32 v51, v116, v50
	s_and_saveexec_b64 s[0:1], s[36:37]
	s_cbranch_execz .LBB0_1620
	s_waitcnt lgkmcnt(0)
	v_add_f32_e32 v50, v50, v51
	v_fma_f32 v50, v50, s6, 0.5
	v_trunc_f32_e32 v50, v50
	v_mul_f32_e32 v51, 0x2f800000, v50
	v_floor_f32_e32 v51, v51
	v_fmac_f32_e32 v50, 0xcf800000, v51
	v_cvt_u32_f32_e32 v50, v50
	v_cvt_u32_f32_e32 v51, v51
	v_lshl_add_u64 v[184:185], v[66:67], 3, s[40:41]
	v_mov_b32_e32 v186, v50
	v_mov_b32_e32 v187, v51
.LBB0_1620:
	s_or_b64 exec, exec, s[0:1]
	v_add_u32_e32 v50, 0x90, v142
	s_waitcnt lgkmcnt(0)
	v_ashrrev_i32_e32 v51, 31, v50
	v_lshlrev_b64 v[52:53], 12, v[50:51]
	v_lshl_add_u64 v[52:53], s[94:95], 0, v[52:53]
	v_lshl_add_u64 v[52:53], v[140:141], 1, v[52:53]
	global_load_dwordx4 v[54:57], v[52:53], off
	s_waitcnt vmcnt(0)
	v_lshlrev_b32_e32 v58, 16, v54
	v_and_b32_e32 v54, 0xffff0000, v54
	v_add_f32_e32 v46, v46, v58
	v_add_f32_e32 v47, v47, v54
	v_cvt_pk_bf16_f32 v46, v46, v47
	v_lshlrev_b32_e32 v47, 16, v55
	v_add_f32_e32 v47, v48, v47
	v_and_b32_e32 v48, 0xffff0000, v55
	v_add_f32_e32 v48, v49, v48
	v_cvt_pk_bf16_f32 v47, v47, v48
	v_lshlrev_b32_e32 v48, 16, v56
	v_add_f32_e32 v42, v42, v48
	v_and_b32_e32 v48, 0xffff0000, v56
	v_add_f32_e32 v43, v43, v48
	v_cvt_pk_bf16_f32 v48, v42, v43
	v_and_b32_e32 v43, 0xffff0000, v57
	v_lshlrev_b32_e32 v42, 16, v57
	v_add_f32_e32 v43, v45, v43
	v_add_f32_e32 v42, v44, v42
	v_cvt_pk_bf16_f32 v49, v42, v43
	v_and_b32_e32 v43, 0xffff0000, v46
	v_lshlrev_b32_e32 v42, 16, v46
	v_and_b32_e32 v45, 0xffff0000, v47
	v_mul_f32_e32 v43, v43, v43
	v_lshlrev_b32_e32 v44, 16, v47
	v_fmac_f32_e32 v43, v42, v42
	v_mul_f32_e32 v42, v45, v45
	global_store_dwordx4 v[52:53], v[46:49], off
	v_fmac_f32_e32 v42, v44, v44
	v_add_f32_e32 v42, v43, v42
	v_lshlrev_b32_e32 v46, 16, v48
	v_and_b32_e32 v47, 0xffff0000, v48
	v_lshlrev_b32_e32 v48, 16, v49
	v_and_b32_e32 v49, 0xffff0000, v49
	v_mul_f32_e32 v43, v47, v47
	v_mul_f32_e32 v44, v49, v49
	v_fmac_f32_e32 v43, v46, v46
	v_fmac_f32_e32 v44, v48, v48
	v_add_f32_e32 v43, v43, v44
	v_add_f32_e32 v46, v42, v43
	global_load_dwordx4 v[42:45], v[52:53], off offset:256
	s_waitcnt vmcnt(0)
	v_lshlrev_b32_e32 v47, 16, v42
	v_and_b32_e32 v42, 0xffff0000, v42
	v_add_f32_e32 v38, v38, v47
	v_add_f32_e32 v39, v39, v42
	v_cvt_pk_bf16_f32 v38, v38, v39
	v_lshlrev_b32_e32 v39, 16, v43
	v_add_f32_e32 v39, v40, v39
	v_and_b32_e32 v40, 0xffff0000, v43
	v_add_f32_e32 v40, v41, v40
	v_cvt_pk_bf16_f32 v39, v39, v40
	v_lshlrev_b32_e32 v40, 16, v44
	v_add_f32_e32 v34, v34, v40
	v_and_b32_e32 v40, 0xffff0000, v44
	v_add_f32_e32 v35, v35, v40
	v_cvt_pk_bf16_f32 v40, v34, v35
	v_and_b32_e32 v35, 0xffff0000, v45
	v_lshlrev_b32_e32 v34, 16, v45
	v_add_f32_e32 v35, v37, v35
	v_add_f32_e32 v34, v36, v34
	v_cvt_pk_bf16_f32 v41, v34, v35
	v_and_b32_e32 v35, 0xffff0000, v38
	v_lshlrev_b32_e32 v34, 16, v38
	v_and_b32_e32 v37, 0xffff0000, v39
	v_mul_f32_e32 v35, v35, v35
	v_lshlrev_b32_e32 v36, 16, v39
	v_fmac_f32_e32 v35, v34, v34
	v_mul_f32_e32 v34, v37, v37
	global_store_dwordx4 v[52:53], v[38:41], off offset:256
	v_fmac_f32_e32 v34, v36, v36
	v_add_f32_e32 v34, v35, v34
	v_lshlrev_b32_e32 v38, 16, v40
	v_and_b32_e32 v39, 0xffff0000, v40
	v_lshlrev_b32_e32 v40, 16, v41
	v_and_b32_e32 v41, 0xffff0000, v41
	v_mul_f32_e32 v35, v39, v39
	v_mul_f32_e32 v36, v41, v41
	v_fmac_f32_e32 v35, v38, v38
	v_fmac_f32_e32 v36, v40, v40
	v_add_f32_e32 v35, v35, v36
	v_add_f32_e32 v34, v34, v35
	v_add_f32_e32 v34, v46, v34
	ds_bpermute_b32 v35, v122, v34
	s_waitcnt lgkmcnt(0)
	v_add_f32_e32 v34, v34, v35
	ds_bpermute_b32 v35, v116, v34
	s_and_saveexec_b64 s[0:1], s[36:37]
	s_cbranch_execz .LBB0_1622
	s_waitcnt lgkmcnt(0)
	v_add_f32_e32 v34, v34, v35
	v_fma_f32 v34, v34, s6, 0.5
	v_trunc_f32_e32 v34, v34
	v_mul_f32_e32 v35, 0x2f800000, v34
	v_floor_f32_e32 v35, v35
	v_fmac_f32_e32 v34, 0xcf800000, v35
	v_cvt_u32_f32_e32 v34, v34
	v_cvt_u32_f32_e32 v35, v35
	v_lshl_add_u64 v[188:189], v[50:51], 3, s[40:41]
	v_mov_b32_e32 v190, v34
	v_mov_b32_e32 v191, v35
.LBB0_1622:
	s_or_b64 exec, exec, s[0:1]
	v_add_u32_e32 v34, 0xa0, v142
	s_waitcnt lgkmcnt(0)
	v_ashrrev_i32_e32 v35, 31, v34
	v_lshlrev_b64 v[36:37], 12, v[34:35]
	v_lshl_add_u64 v[36:37], s[94:95], 0, v[36:37]
	v_lshl_add_u64 v[36:37], v[140:141], 1, v[36:37]
	global_load_dwordx4 v[38:41], v[36:37], off
	s_waitcnt vmcnt(0)
	v_lshlrev_b32_e32 v42, 16, v38
	v_and_b32_e32 v38, 0xffff0000, v38
	v_add_f32_e32 v30, v30, v42
	v_add_f32_e32 v31, v31, v38
	v_cvt_pk_bf16_f32 v30, v30, v31
	v_lshlrev_b32_e32 v31, 16, v39
	v_add_f32_e32 v31, v32, v31
	v_and_b32_e32 v32, 0xffff0000, v39
	v_add_f32_e32 v32, v33, v32
	v_cvt_pk_bf16_f32 v31, v31, v32
	v_lshlrev_b32_e32 v32, 16, v40
	v_add_f32_e32 v26, v26, v32
	v_and_b32_e32 v32, 0xffff0000, v40
	v_add_f32_e32 v27, v27, v32
	v_cvt_pk_bf16_f32 v32, v26, v27
	v_and_b32_e32 v27, 0xffff0000, v41
	v_lshlrev_b32_e32 v26, 16, v41
	v_add_f32_e32 v27, v29, v27
	v_add_f32_e32 v26, v28, v26
	v_cvt_pk_bf16_f32 v33, v26, v27
	v_and_b32_e32 v27, 0xffff0000, v30
	v_lshlrev_b32_e32 v26, 16, v30
	v_and_b32_e32 v29, 0xffff0000, v31
	v_mul_f32_e32 v27, v27, v27
	v_lshlrev_b32_e32 v28, 16, v31
	v_fmac_f32_e32 v27, v26, v26
	v_mul_f32_e32 v26, v29, v29
	global_store_dwordx4 v[36:37], v[30:33], off
	v_fmac_f32_e32 v26, v28, v28
	v_add_f32_e32 v26, v27, v26
	v_lshlrev_b32_e32 v30, 16, v32
	v_and_b32_e32 v31, 0xffff0000, v32
	v_lshlrev_b32_e32 v32, 16, v33
	v_and_b32_e32 v33, 0xffff0000, v33
	v_mul_f32_e32 v27, v31, v31
	v_mul_f32_e32 v28, v33, v33
	v_fmac_f32_e32 v27, v30, v30
	v_fmac_f32_e32 v28, v32, v32
	v_add_f32_e32 v27, v27, v28
	v_add_f32_e32 v30, v26, v27
	global_load_dwordx4 v[26:29], v[36:37], off offset:256
	s_waitcnt vmcnt(0)
	v_lshlrev_b32_e32 v31, 16, v26
	v_and_b32_e32 v26, 0xffff0000, v26
	v_add_f32_e32 v22, v22, v31
	v_add_f32_e32 v23, v23, v26
	v_cvt_pk_bf16_f32 v22, v22, v23
	v_lshlrev_b32_e32 v23, 16, v27
	v_add_f32_e32 v23, v24, v23
	v_and_b32_e32 v24, 0xffff0000, v27
	v_add_f32_e32 v24, v25, v24
	v_cvt_pk_bf16_f32 v23, v23, v24
	v_lshlrev_b32_e32 v24, 16, v28
	v_add_f32_e32 v18, v18, v24
	v_and_b32_e32 v24, 0xffff0000, v28
	v_add_f32_e32 v19, v19, v24
	v_cvt_pk_bf16_f32 v24, v18, v19
	v_and_b32_e32 v19, 0xffff0000, v29
	v_lshlrev_b32_e32 v18, 16, v29
	v_add_f32_e32 v19, v21, v19
	v_add_f32_e32 v18, v20, v18
	v_cvt_pk_bf16_f32 v25, v18, v19
	v_and_b32_e32 v19, 0xffff0000, v22
	v_lshlrev_b32_e32 v18, 16, v22
	v_and_b32_e32 v21, 0xffff0000, v23
	v_mul_f32_e32 v19, v19, v19
	v_lshlrev_b32_e32 v20, 16, v23
	v_fmac_f32_e32 v19, v18, v18
	v_mul_f32_e32 v18, v21, v21
	global_store_dwordx4 v[36:37], v[22:25], off offset:256
	v_fmac_f32_e32 v18, v20, v20
	v_add_f32_e32 v18, v19, v18
	v_lshlrev_b32_e32 v22, 16, v24
	v_and_b32_e32 v23, 0xffff0000, v24
	v_lshlrev_b32_e32 v24, 16, v25
	v_and_b32_e32 v25, 0xffff0000, v25
	v_mul_f32_e32 v19, v23, v23
	v_mul_f32_e32 v20, v25, v25
	v_fmac_f32_e32 v19, v22, v22
	v_fmac_f32_e32 v20, v24, v24
	v_add_f32_e32 v19, v19, v20
	v_add_f32_e32 v18, v18, v19
	v_add_f32_e32 v18, v30, v18
	ds_bpermute_b32 v19, v122, v18
	s_waitcnt lgkmcnt(0)
	v_add_f32_e32 v18, v18, v19
	ds_bpermute_b32 v19, v116, v18
	s_and_saveexec_b64 s[0:1], s[36:37]
	s_cbranch_execz .LBB0_1624
	s_waitcnt lgkmcnt(0)
	v_add_f32_e32 v18, v18, v19
	v_fma_f32 v18, v18, s6, 0.5
	v_trunc_f32_e32 v18, v18
	v_mul_f32_e32 v19, 0x2f800000, v18
	v_floor_f32_e32 v19, v19
	v_fmac_f32_e32 v18, 0xcf800000, v19
	v_cvt_u32_f32_e32 v18, v18
	v_cvt_u32_f32_e32 v19, v19
	v_lshl_add_u64 v[192:193], v[34:35], 3, s[40:41]
	v_mov_b32_e32 v194, v18
	v_mov_b32_e32 v195, v19

.LBB0_1626:
	s_or_b64 exec, exec, s[0:1]
	s_and_saveexec_b64 s[0:1], s[36:37]
	global_atomic_add_x2 v[168:169], v[170:171], off
	global_atomic_add_x2 v[172:173], v[174:175], off
	global_atomic_add_x2 v[176:177], v[178:179], off
	global_atomic_add_x2 v[180:181], v[182:183], off
	global_atomic_add_x2 v[184:185], v[186:187], off
	global_atomic_add_x2 v[188:189], v[190:191], off
	global_atomic_add_x2 v[192:193], v[194:195], off
	s_or_b64 exec, exec, s[0:1]
	s_and_b64 vcc, exec, s[38:39]
	s_mov_b64 s[0:1], -1
	s_cbranch_vccnz .LBB0_1603
	s_andn2_b64 vcc, exec, s[20:21]
	s_cbranch_vccnz .LBB0_1602
	s_barrier
	s_branch .LBB0_1602
